# wave-priority removal: the s_setprio pairs around the MLA and NA attention MFMA clusters deleted (equal priority for both waves of a SIMD)
# baseline (speedup 1.0000x reference)
; DI f32x16 mfma32(bf16x8 a, bf16x8 b, f32x16 c) { return __builtin_amdgcn_mfma_f32_32x32x16_bf16(a, b, c, 0, 0, 0); }
; DI bool softmax_tile(f32x16& s0, f32x16& s1, float& m, float& l, float& alpha, bf16x8* pf, int lane, bool first, bool check) {
;   if (first) {
;     float mx = fmaxf(s0[0], s1[0]);
; #pragma unroll
;     for (int i = 1; i < 16; ++i) mx = fmaxf(mx, fmaxf(s0[i], s1[i]));
;     mx = fmaxf(mx, shx(mx, 32, lane));
;     m += mx;
; #pragma unroll
;     for (int i = 0; i < 16; ++i) { s0[i] -= mx; s1[i] -= mx; }
;   }
; DI void attn_mla_unit(const Params& p, int b, int h, int qb, char* smem, bool pre, int nh, bool has_next) {
;     ...
;   __syncthreads();
;   if (!pre) put_stage(smem);
;   __syncthreads();
;   get_stage(1);
;   for (int kt = 0; kt < 32; ++kt) {
;     const char* ks = smem + (kt & 1) * STG; const char* vs = ks + 128 * KR;
; #pragma unroll
;     for (int sub = 0; sub < 2; ++sub) {
;       f32x16 s0, s1;
; #pragma unroll
;       for (int i = 0; i < 16; ++i) { s0[i] = -m; s1[i] = -m; }
;       {
;         bf16x8 kf[12];
; #pragma unroll
;         for (int s = 0; s < 6; ++s) {
;           kf[2 * s] = *(const bf16x8*)(ks + (sub * 64 + r32) * KR + (s * 16 + hh * 8) * 2);
;           kf[2 * s + 1] = *(const bf16x8*)(ks + (sub * 64 + 32 + r32) * KR + (s * 16 + hh * 8) * 2);
;         }
;         __builtin_amdgcn_sched_barrier(0); __builtin_amdgcn_s_setprio(1);
; #pragma unroll
;         for (int s = 0; s < 6; ++s) { s0 = mfma32(kf[2 * s], qf[s], s0); s1 = mfma32(kf[2 * s + 1], qf[s], s1); }
;       __builtin_amdgcn_s_setprio(0);
; }
;       float alpha; bf16x8 pf[4];
;       const bool resc = softmax_tile(s0, s1, m, l, alpha, pf, lane, (kt == 0) && (sub == 0), (sub == 0) && ((kt & 3) == 0));
.LBB0_1479:
	s_waitcnt vmcnt(4)
	v_and_b32_e32 v0, 63, v22
	v_bfe_u32 v2, v22, 2, 2
	v_lshrrev_b32_e32 v3, 3, v22
	v_and_b32_e32 v1, 16, v22
	v_and_or_b32 v34, v3, 4, v2
	v_lshlrev_b32_e32 v2, 2, v0
	v_and_or_b32 v0, v2, 12, v1
	v_lshlrev_b32_e32 v147, 1, v0
	v_add_co_u32_e32 v0, vcc, 0x20000, v128
	s_waitcnt lgkmcnt(0)
	s_nop 0
	v_addc_co_u32_e32 v1, vcc, 0, v129, vcc
	s_barrier
	global_load_dwordx4 v[64:67], v[0:1], off
	v_add_co_u32_e32 v0, vcc, 0x20000, v130
	v_xor_b32_e32 v140, 0x80, v2
	s_nop 0
	v_addc_co_u32_e32 v1, vcc, 0, v131, vcc
	global_load_dwordx4 v[68:71], v[0:1], off
	v_add_co_u32_e32 v0, vcc, 0x30000, v128
	s_nop 1
	v_addc_co_u32_e32 v1, vcc, 0, v129, vcc
	global_load_dwordx4 v[72:75], v[0:1], off
	v_add_co_u32_e32 v0, vcc, 0x30000, v130
	s_nop 1
	v_addc_co_u32_e32 v1, vcc, 0, v131, vcc
	global_load_dwordx4 v[76:79], v[0:1], off
	v_add_co_u32_e32 v0, vcc, 0x2000, v126
	s_nop 1
	v_addc_co_u32_e32 v1, vcc, 0, v127, vcc
	global_load_dwordx4 v[104:107], v[0:1], off
	v_mad_u32_u24 v0, v34, s46, 0
	v_add_u32_e32 v108, v0, v147
	v_mad_u32_u24 v0, v33, s47, 0
	v_add_u32_e32 v141, v0, v144
	ds_read_b128 v[36:39], v141 offset:6656
	ds_read_b128 v[40:43], v141
	ds_read_b128 v[44:47], v141 offset:32
	ds_read_b128 v[48:51], v141 offset:6688
	ds_read_b128 v[52:55], v141 offset:64
	ds_read_b128 v[56:59], v141 offset:6720
	ds_read_b128 v[60:63], v141 offset:96
	ds_read_b128 v[110:113], v141 offset:6752
	ds_read_b128 v[114:117], v141 offset:128
	ds_read_b128 v[118:121], v141 offset:6784
	ds_read_b128 v[148:151], v141 offset:160
	ds_read_b128 v[152:155], v141 offset:6816
	s_mov_b32 s22, s8
	s_mov_b32 s23, s8
	s_mov_b32 s9, s8
	s_mov_b32 s10, s8
	s_mov_b32 s11, s8
	s_mov_b32 s12, s8
	s_mov_b32 s13, s8
	s_mov_b32 s14, s8
	s_mov_b32 s15, s8
	s_mov_b32 s16, s8
	s_mov_b32 s17, s8
	s_mov_b32 s18, s8
	s_mov_b32 s19, s8
	s_mov_b32 s20, s8
	s_mov_b32 s21, s8
	s_waitcnt vmcnt(5)
	v_mov_b64_e32 v[30:31], s[22:23]
	v_mov_b64_e32 v[28:29], s[20:21]
	v_mov_b64_e32 v[26:27], s[18:19]
	v_mov_b64_e32 v[24:25], s[16:17]
	v_mov_b64_e32 v[22:23], s[14:15]
	v_mov_b64_e32 v[20:21], s[12:13]
	v_mov_b64_e32 v[18:19], s[10:11]
	v_mov_b64_e32 v[16:17], s[8:9]
	s_waitcnt lgkmcnt(10)
	s_nop 0
	v_mfma_f32_32x32x16_bf16 v[0:15], v[40:43], v[100:103], v[16:31]
	v_mfma_f32_32x32x16_bf16 v[16:31], v[36:39], v[100:103], v[16:31]
	s_waitcnt lgkmcnt(9)
	v_mfma_f32_32x32x16_bf16 v[0:15], v[44:47], v[96:99], v[0:15]
	s_waitcnt lgkmcnt(8)
	v_mfma_f32_32x32x16_bf16 v[16:31], v[48:51], v[96:99], v[16:31]
	s_waitcnt lgkmcnt(7)
	v_mfma_f32_32x32x16_bf16 v[0:15], v[52:55], v[92:95], v[0:15]
	s_waitcnt lgkmcnt(6)
	v_mfma_f32_32x32x16_bf16 v[16:31], v[56:59], v[92:95], v[16:31]
	s_waitcnt lgkmcnt(5)
	v_mfma_f32_32x32x16_bf16 v[0:15], v[60:63], v[88:91], v[0:15]
	s_waitcnt lgkmcnt(4)
	v_mfma_f32_32x32x16_bf16 v[16:31], v[110:113], v[88:91], v[16:31]
	s_waitcnt lgkmcnt(3)
	v_mfma_f32_32x32x16_bf16 v[0:15], v[114:117], v[84:87], v[0:15]
	s_waitcnt lgkmcnt(2)
	v_mfma_f32_32x32x16_bf16 v[16:31], v[118:121], v[84:87], v[16:31]
	s_waitcnt lgkmcnt(1)
	v_mfma_f32_32x32x16_bf16 v[0:15], v[148:151], v[80:83], v[0:15]
	s_waitcnt lgkmcnt(0)
	v_mfma_f32_32x32x16_bf16 v[16:31], v[152:155], v[80:83], v[16:31]
	s_nop 10
	v_max_f32_e32 v32, v17, v17
	v_max_f32_e32 v35, v1, v1
	v_max_f32_e32 v32, v35, v32
	v_max_f32_e32 v35, v18, v18
	v_max_f32_e32 v36, v2, v2
	v_max_f32_e32 v35, v36, v35
	v_max_f32_e32 v36, v19, v19
	v_max_f32_e32 v37, v3, v3
	v_max3_f32 v32, v0, v16, v32
	v_max_f32_e32 v36, v37, v36
	v_max3_f32 v32, v32, v35, v36
	v_max_f32_e32 v35, v20, v20
	v_max_f32_e32 v36, v4, v4
	v_max_f32_e32 v35, v36, v35
	v_max_f32_e32 v36, v21, v21
	v_max_f32_e32 v37, v5, v5
	v_max_f32_e32 v36, v37, v36
	v_max3_f32 v32, v32, v35, v36
	v_max_f32_e32 v35, v22, v22
	v_max_f32_e32 v36, v6, v6
	v_max_f32_e32 v35, v36, v35
	v_max_f32_e32 v36, v23, v23
	v_max_f32_e32 v37, v7, v7
	v_max_f32_e32 v36, v37, v36
	v_max3_f32 v32, v32, v35, v36
	v_max_f32_e32 v35, v24, v24
	v_max_f32_e32 v36, v8, v8
	v_max_f32_e32 v35, v36, v35
	v_max_f32_e32 v36, v25, v25
	v_max_f32_e32 v37, v9, v9
	v_max_f32_e32 v36, v37, v36
	v_max3_f32 v32, v32, v35, v36
	v_max_f32_e32 v35, v26, v26
	v_max_f32_e32 v36, v10, v10
	v_max_f32_e32 v35, v36, v35
	v_max_f32_e32 v36, v27, v27
	v_max_f32_e32 v37, v11, v11
	v_max_f32_e32 v36, v37, v36
	v_max3_f32 v32, v32, v35, v36
	v_max_f32_e32 v35, v28, v28
	v_max_f32_e32 v36, v12, v12
	v_max_f32_e32 v35, v36, v35
	v_max_f32_e32 v36, v29, v29
	v_max_f32_e32 v37, v13, v13
	v_max_f32_e32 v36, v37, v36
	v_max3_f32 v32, v32, v35, v36
	v_max_f32_e32 v35, v30, v30
	v_max_f32_e32 v36, v14, v14
	v_max_f32_e32 v35, v36, v35
	v_max_f32_e32 v36, v31, v31
	v_max_f32_e32 v37, v15, v15
	v_max_f32_e32 v36, v37, v36
	v_max3_f32 v32, v32, v35, v36
	ds_bpermute_b32 v35, v140, v32
	s_waitcnt lgkmcnt(0)
; DI f32x16 mfma32(bf16x8 a, bf16x8 b, f32x16 c) { return __builtin_amdgcn_mfma_f32_32x32x16_bf16(a, b, c, 0, 0, 0); }
; DI bool softmax_tile(f32x16& s0, f32x16& s1, float& m, float& l, float& alpha, bf16x8* pf, int lane, bool first, bool check) {
;     ...
;   float sum = 0.f;
; #pragma unroll
;   for (int i = 0; i < 16; ++i) { s0[i] = __builtin_amdgcn_exp2f(s0[i]); sum += s0[i]; }
; #pragma unroll
;   for (int i = 0; i < 16; ++i) { s1[i] = __builtin_amdgcn_exp2f(s1[i]); sum += s1[i]; }
;   l += sum;
;   pf[0] = pack8(s0, 0); pf[1] = pack8(s0, 8); pf[2] = pack8(s1, 0); pf[3] = pack8(s1, 8);
;   alpha = 1.f;
;   if (!check) return false;
;   const float rsum = sum + shx(sum, 32, lane);
;   const bool trig = rsum > 65536.f;
;   const bool resc = (__builtin_amdgcn_ballot_w64(trig) != 0ull);
;   alpha = 1.f;
;   if (resc) {
;     const float d = trig ? (float)(__builtin_amdgcn_frexp_expf(rsum) - 7) : 0.f;
;     alpha = __builtin_amdgcn_exp2f(-d);
;     m += d; l *= alpha;
;   }
;   return resc;
; }
; DI void attn_mla_unit(const Params& p, int b, int h, int qb, char* smem, bool pre, int nh, bool has_next) {
;     ...
;         bf16x8 vf[8];
; #pragma unroll
;         for (int s = 0; s < 4; ++s) { vf[2 * s] = ld_vfrag_tr(vs, vbase, VR, sub * 64 + 16 * s, 0); vf[2 * s + 1] = ld_vfrag_tr(vs, vbase, VR, sub * 64 + 16 * s, 32); }
;         __builtin_amdgcn_sched_barrier(0); __builtin_amdgcn_s_setprio(1);
; #pragma unroll
;         for (int s = 0; s < 4; ++s) { O0 = mfma32(vf[2 * s], pf[s], O0); O1 = mfma32(vf[2 * s + 1], pf[s], O1); }
;       __builtin_amdgcn_s_setprio(0);
; }
;       if (resc) { scale16(O0, alpha); scale16(O1, alpha); }
	v_max_f32_e32 v35, v35, v35
	v_max_f32_e32 v35, v32, v35
	v_sub_f32_e32 v0, v0, v35
	v_sub_f32_e32 v1, v1, v35
	v_exp_f32_e32 v0, v0
	v_sub_f32_e32 v2, v2, v35
	v_exp_f32_e32 v1, v1
	v_sub_f32_e32 v3, v3, v35
	v_exp_f32_e32 v2, v2
	v_sub_f32_e32 v4, v4, v35
	v_exp_f32_e32 v3, v3
	v_sub_f32_e32 v5, v5, v35
	v_add_f32_e32 v32, 0, v0
	v_exp_f32_e32 v4, v4
	v_sub_f32_e32 v6, v6, v35
	v_add_f32_e32 v32, v1, v32
	v_exp_f32_e32 v5, v5
	v_sub_f32_e32 v7, v7, v35
	v_add_f32_e32 v32, v2, v32
	v_exp_f32_e32 v6, v6
	v_sub_f32_e32 v8, v8, v35
	v_add_f32_e32 v32, v3, v32
	v_exp_f32_e32 v7, v7
	v_sub_f32_e32 v9, v9, v35
	v_add_f32_e32 v32, v4, v32
	v_exp_f32_e32 v8, v8
	v_sub_f32_e32 v10, v10, v35
	v_add_f32_e32 v32, v5, v32
	v_exp_f32_e32 v9, v9
	v_sub_f32_e32 v11, v11, v35
	v_add_f32_e32 v32, v6, v32
	v_exp_f32_e32 v10, v10
	v_sub_f32_e32 v12, v12, v35
	v_add_f32_e32 v32, v7, v32
	v_exp_f32_e32 v11, v11
	v_sub_f32_e32 v13, v13, v35
	v_add_f32_e32 v32, v8, v32
	v_exp_f32_e32 v12, v12
	v_sub_f32_e32 v14, v14, v35
	v_add_f32_e32 v32, v9, v32
	v_exp_f32_e32 v13, v13
	v_sub_f32_e32 v15, v15, v35
	v_add_f32_e32 v32, v10, v32
	v_exp_f32_e32 v14, v14
	v_sub_f32_e32 v16, v16, v35
	v_add_f32_e32 v32, v11, v32
	v_exp_f32_e32 v15, v15
	v_sub_f32_e32 v17, v17, v35
	v_add_f32_e32 v32, v12, v32
	v_exp_f32_e32 v16, v16
	v_sub_f32_e32 v18, v18, v35
	v_add_f32_e32 v32, v13, v32
	v_exp_f32_e32 v17, v17
	v_sub_f32_e32 v19, v19, v35
	v_add_f32_e32 v32, v14, v32
	v_exp_f32_e32 v18, v18
	v_sub_f32_e32 v20, v20, v35
	v_add_f32_e32 v32, v15, v32
	v_exp_f32_e32 v19, v19
	v_sub_f32_e32 v21, v21, v35
	v_add_f32_e32 v32, v16, v32
	v_exp_f32_e32 v20, v20
	v_sub_f32_e32 v22, v22, v35
	v_add_f32_e32 v32, v17, v32
	v_exp_f32_e32 v21, v21
	v_sub_f32_e32 v23, v23, v35
	v_add_f32_e32 v32, v18, v32
	v_exp_f32_e32 v22, v22
	v_sub_f32_e32 v24, v24, v35
	v_add_f32_e32 v32, v19, v32
	v_exp_f32_e32 v23, v23
	v_sub_f32_e32 v25, v25, v35
	v_add_f32_e32 v32, v20, v32
	v_exp_f32_e32 v24, v24
	v_sub_f32_e32 v26, v26, v35
	v_add_f32_e32 v32, v21, v32
	v_exp_f32_e32 v25, v25
	v_sub_f32_e32 v27, v27, v35
	v_add_f32_e32 v32, v22, v32
	v_exp_f32_e32 v26, v26
	v_sub_f32_e32 v28, v28, v35
	v_add_f32_e32 v32, v23, v32
	v_exp_f32_e32 v27, v27
	v_sub_f32_e32 v29, v29, v35
	v_add_f32_e32 v32, v24, v32
	v_exp_f32_e32 v28, v28
	v_sub_f32_e32 v30, v30, v35
	v_add_f32_e32 v32, v25, v32
	v_exp_f32_e32 v29, v29
	v_sub_f32_e32 v31, v31, v35
	v_add_f32_e32 v32, v26, v32
	v_exp_f32_e32 v30, v30
	v_add_f32_e32 v32, v27, v32
	v_exp_f32_e32 v31, v31
	v_add_f32_e32 v32, v28, v32
	v_add_f32_e32 v32, v29, v32
	v_add_f32_e32 v32, v30, v32
	v_add_f32_e32 v36, v31, v32
	v_cvt_pk_bf16_f32 v0, v0, v1
	v_cvt_pk_bf16_f32 v1, v2, v3
	v_cvt_pk_bf16_f32 v2, v4, v5
	ds_bpermute_b32 v4, v140, v36
	v_cvt_pk_bf16_f32 v3, v6, v7
	v_cvt_pk_bf16_f32 v38, v8, v9
	v_cvt_pk_bf16_f32 v39, v10, v11
	v_cvt_pk_bf16_f32 v40, v12, v13
	s_waitcnt lgkmcnt(0)
	v_add_f32_e32 v4, v36, v4
	v_cmp_lt_f32_e32 vcc, s88, v4
	v_frexp_exp_i32_f32_e32 v4, v4
	v_add_u32_e32 v4, -7, v4
	v_cvt_f32_i32_e32 v4, v4
	s_cmp_eq_u64 vcc, 0
	s_cselect_b64 s[2:3], -1, 0
	v_cvt_pk_bf16_f32 v41, v14, v15
	v_cndmask_b32_e32 v37, 0, v4, vcc
	ds_read_b64_tr_b16 v[4:5], v108 offset:26624
	ds_read_b64_tr_b16 v[6:7], v108 offset:28160
	ds_read_b64_tr_b16 v[8:9], v108 offset:26688
	ds_read_b64_tr_b16 v[10:11], v108 offset:28224
	ds_read_b64_tr_b16 v[50:51], v108 offset:29696
	ds_read_b64_tr_b16 v[52:53], v108 offset:31232
	ds_read_b64_tr_b16 v[54:55], v108 offset:29760
	ds_read_b64_tr_b16 v[56:57], v108 offset:31296
	ds_read_b64_tr_b16 v[58:59], v108 offset:32768
	ds_read_b64_tr_b16 v[60:61], v108 offset:34304
	ds_read_b64_tr_b16 v[110:111], v108 offset:32832
	ds_read_b64_tr_b16 v[112:113], v108 offset:34368
	ds_read_b64_tr_b16 v[114:115], v108 offset:35840
	ds_read_b64_tr_b16 v[116:117], v108 offset:37376
	ds_read_b64_tr_b16 v[118:119], v108 offset:35904
	ds_read_b64_tr_b16 v[120:121], v108 offset:37440
	v_exp_f32_e64 v32, -v37
	v_cvt_pk_bf16_f32 v42, v16, v17
	v_cvt_pk_bf16_f32 v43, v18, v19
	v_cvt_pk_bf16_f32 v44, v20, v21
	v_cvt_pk_bf16_f32 v45, v22, v23
	v_cvt_pk_bf16_f32 v46, v24, v25
	v_cvt_pk_bf16_f32 v47, v26, v27
	v_cvt_pk_bf16_f32 v48, v28, v29
	v_cvt_pk_bf16_f32 v49, v30, v31
	s_waitcnt lgkmcnt(14)
	v_mfma_f32_32x32x16_bf16 v[16:31], v[4:7], v[0:3], 0
	s_waitcnt lgkmcnt(12)
	v_mfma_f32_32x32x16_bf16 v[0:15], v[8:11], v[0:3], 0
	s_waitcnt lgkmcnt(10)
	v_mfma_f32_32x32x16_bf16 v[16:31], v[50:53], v[38:41], v[16:31]
	s_waitcnt lgkmcnt(8)
	v_mfma_f32_32x32x16_bf16 v[0:15], v[54:57], v[38:41], v[0:15]
	s_waitcnt lgkmcnt(6)
	v_mfma_f32_32x32x16_bf16 v[16:31], v[58:61], v[42:45], v[16:31]
	s_waitcnt lgkmcnt(4)
	v_mfma_f32_32x32x16_bf16 v[0:15], v[110:113], v[42:45], v[0:15]
	s_waitcnt lgkmcnt(2)
	v_mfma_f32_32x32x16_bf16 v[16:31], v[114:117], v[46:49], v[16:31]
	s_waitcnt lgkmcnt(0)
	v_mfma_f32_32x32x16_bf16 v[0:15], v[118:121], v[46:49], v[0:15]
	s_cbranch_vccz .LBB0_1481
	s_nop 7
	v_pk_mul_f32 v[30:31], v[30:31], v[32:33] op_sel_hi:[1,0]
	v_pk_mul_f32 v[28:29], v[28:29], v[32:33] op_sel_hi:[1,0]
	v_pk_mul_f32 v[26:27], v[26:27], v[32:33] op_sel_hi:[1,0]
	v_pk_mul_f32 v[24:25], v[24:25], v[32:33] op_sel_hi:[1,0]
	v_pk_mul_f32 v[22:23], v[22:23], v[32:33] op_sel_hi:[1,0]
	v_pk_mul_f32 v[20:21], v[20:21], v[32:33] op_sel_hi:[1,0]
	v_pk_mul_f32 v[18:19], v[18:19], v[32:33] op_sel_hi:[1,0]
	v_pk_mul_f32 v[16:17], v[16:17], v[32:33] op_sel_hi:[1,0]
	v_pk_mul_f32 v[14:15], v[14:15], v[32:33] op_sel_hi:[1,0]
	v_pk_mul_f32 v[12:13], v[12:13], v[32:33] op_sel_hi:[1,0]
	v_pk_mul_f32 v[10:11], v[10:11], v[32:33] op_sel_hi:[1,0]
	v_pk_mul_f32 v[8:9], v[8:9], v[32:33] op_sel_hi:[1,0]
	v_pk_mul_f32 v[6:7], v[6:7], v[32:33] op_sel_hi:[1,0]
	v_pk_mul_f32 v[4:5], v[4:5], v[32:33] op_sel_hi:[1,0]
	v_pk_mul_f32 v[2:3], v[2:3], v[32:33] op_sel_hi:[1,0]
	v_pk_mul_f32 v[0:1], v[0:1], v[32:33] op_sel_hi:[1,0]
; DI f32x16 mfma32(bf16x8 a, bf16x8 b, f32x16 c) { return __builtin_amdgcn_mfma_f32_32x32x16_bf16(a, b, c, 0, 0, 0); }
; DI void attn_mla_unit(const Params& p, int b, int h, int qb, char* smem, bool pre, int nh, bool has_next) {
;     ...
;     for (int sub = 0; sub < 2; ++sub) {
;       f32x16 s0, s1;
; #pragma unroll
;       for (int i = 0; i < 16; ++i) { s0[i] = -m; s1[i] = -m; }
;       {
;         bf16x8 kf[12];
; #pragma unroll
;         for (int s = 0; s < 6; ++s) {
;           kf[2 * s] = *(const bf16x8*)(ks + (sub * 64 + r32) * KR + (s * 16 + hh * 8) * 2);
;           kf[2 * s + 1] = *(const bf16x8*)(ks + (sub * 64 + 32 + r32) * KR + (s * 16 + hh * 8) * 2);
;         }
;         __builtin_amdgcn_sched_barrier(0); __builtin_amdgcn_s_setprio(1);
; #pragma unroll
;         for (int s = 0; s < 6; ++s) { s0 = mfma32(kf[2 * s], qf[s], s0); s1 = mfma32(kf[2 * s + 1], qf[s], s1); }
;       __builtin_amdgcn_s_setprio(0);
; }
;       float alpha; bf16x8 pf[4];
;       const bool resc = softmax_tile(s0, s1, m, l, alpha, pf, lane, (kt == 0) && (sub == 0), (sub == 0) && ((kt & 3) == 0));
;       {
;         bf16x8 vf[8];
; #pragma unroll
;         for (int s = 0; s < 4; ++s) { vf[2 * s] = ld_vfrag_tr(vs, vbase, VR, sub * 64 + 16 * s, 0); vf[2 * s + 1] = ld_vfrag_tr(vs, vbase, VR, sub * 64 + 16 * s, 32); }
.LBB0_1481:
	ds_read_b128 v[110:113], v141 offset:13312
	ds_read_b128 v[114:117], v141 offset:13344
	ds_read_b128 v[118:121], v141 offset:19968
	ds_read_b128 v[152:155], v141 offset:20000
	ds_read_b128 v[156:159], v141 offset:13376
	ds_read_b128 v[160:163], v141 offset:13408
	ds_read_b128 v[164:167], v141 offset:20032
	ds_read_b128 v[168:171], v141 offset:20064
	ds_read_b128 v[172:175], v141 offset:13440
	ds_read_b128 v[176:179], v141 offset:13472
	ds_read_b128 v[196:199], v141 offset:20096
	ds_read_b128 v[200:203], v141 offset:20128
	s_add_i32 s34, s34, s44
	s_lshr_b32 s10, s34, 4
	s_sub_i32 s10, s10, s35
	s_lshl_b32 s14, s10, 6
	s_lshl_b32 s9, s35, 6
	v_mul_u32_u24_e32 v149, 0xd0, v33
	s_ashr_i32 s15, s14, 31
	v_add_f32_e32 v33, 0, v35
	v_mul_u32_u24_e32 v148, 0xc0, v34
	v_add_f32_e32 v34, 0, v36
	v_add_f32_e32 v35, v33, v37
	s_cmpk_lt_u32 s34, 0x80
	v_mul_f32_e32 v32, v34, v32
	v_cndmask_b32_e64 v150, v35, v33, s[2:3]
	s_cselect_b64 s[10:11], -1, 0
	s_cmpk_gt_u32 s34, 0x7f
	v_ashrrev_i32_e32 v125, 31, v124
	v_add_u32_e32 v109, 0, v142
	v_add_u32_e32 v122, 0, v143
	v_cndmask_b32_e64 v123, v32, v34, s[2:3]
	s_cselect_b64 s[2:3], -1, 0
	v_xor_b32_e32 v32, 0x80000000, v150
	v_mov_b32_e32 v33, v32
	v_mov_b64_e32 v[220:221], v[32:33]
	v_mov_b64_e32 v[222:223], v[32:33]
	v_mov_b64_e32 v[224:225], v[32:33]
	v_mov_b64_e32 v[226:227], v[32:33]
	v_mov_b64_e32 v[228:229], v[32:33]
	v_mov_b64_e32 v[230:231], v[32:33]
	v_mov_b64_e32 v[232:233], v[32:33]
	v_mov_b64_e32 v[234:235], v[32:33]
	v_mov_b32_e32 v34, v32
	v_mov_b32_e32 v35, v32
	v_mov_b32_e32 v36, v32
	v_mov_b32_e32 v37, v32
	v_mov_b32_e32 v38, v32
	v_mov_b32_e32 v39, v32
	v_mov_b32_e32 v40, v32
	v_mov_b32_e32 v41, v32
	v_mov_b32_e32 v42, v32
	v_mov_b32_e32 v43, v32
	v_mov_b32_e32 v44, v32
	v_mov_b32_e32 v45, v32
	v_mov_b32_e32 v46, v32
	v_mov_b32_e32 v47, v32
	s_waitcnt lgkmcnt(11)
	v_mfma_f32_32x32x16_bf16 v[48:63], v[110:113], v[100:103], v[32:47]
	s_waitcnt lgkmcnt(9)
	v_mfma_f32_32x32x16_bf16 v[32:47], v[118:121], v[100:103], v[32:47]
	v_mfma_f32_32x32x16_bf16 v[48:63], v[114:117], v[96:99], v[48:63]
	s_waitcnt lgkmcnt(8)
	v_mfma_f32_32x32x16_bf16 v[32:47], v[152:155], v[96:99], v[32:47]
	s_waitcnt lgkmcnt(7)
	v_mfma_f32_32x32x16_bf16 v[48:63], v[156:159], v[92:95], v[48:63]
	s_waitcnt lgkmcnt(5)
	v_mfma_f32_32x32x16_bf16 v[32:47], v[164:167], v[92:95], v[32:47]
	v_mfma_f32_32x32x16_bf16 v[48:63], v[160:163], v[88:91], v[48:63]
	s_waitcnt lgkmcnt(4)
	v_mfma_f32_32x32x16_bf16 v[32:47], v[168:171], v[88:91], v[32:47]
	s_waitcnt lgkmcnt(3)
	v_mfma_f32_32x32x16_bf16 v[48:63], v[172:175], v[84:87], v[48:63]
	s_waitcnt lgkmcnt(1)
	v_mfma_f32_32x32x16_bf16 v[32:47], v[196:199], v[84:87], v[32:47]
	v_mfma_f32_32x32x16_bf16 v[48:63], v[176:179], v[80:83], v[48:63]
	s_waitcnt lgkmcnt(0)
	v_mfma_f32_32x32x16_bf16 v[32:47], v[200:203], v[80:83], v[32:47]
	s_nop 8
	v_exp_f32_e32 v48, v48
	v_exp_f32_e32 v49, v49
	v_exp_f32_e32 v50, v50
	v_exp_f32_e32 v51, v51
	v_add_f32_e32 v110, 0, v48
	v_exp_f32_e32 v52, v52
	v_add_f32_e32 v110, v49, v110
	v_exp_f32_e32 v53, v53
	v_add_f32_e32 v110, v50, v110
	v_exp_f32_e32 v54, v54
	v_add_f32_e32 v110, v51, v110
	v_exp_f32_e32 v55, v55
	v_add_f32_e32 v110, v52, v110
	v_exp_f32_e32 v56, v56
	v_add_f32_e32 v110, v53, v110
	v_exp_f32_e32 v57, v57
	v_add_f32_e32 v110, v54, v110
	v_exp_f32_e32 v58, v58
	v_add_f32_e32 v110, v55, v110
	v_exp_f32_e32 v59, v59
	v_add_f32_e32 v110, v56, v110
	v_exp_f32_e32 v60, v60
	v_add_f32_e32 v110, v57, v110
	v_exp_f32_e32 v61, v61
	v_add_f32_e32 v110, v58, v110
	v_exp_f32_e32 v62, v62
	v_add_f32_e32 v110, v59, v110
	v_exp_f32_e32 v63, v63
	v_add_f32_e32 v110, v60, v110
	v_exp_f32_e32 v111, v32
	v_add_f32_e32 v110, v61, v110
	v_add_f32_e32 v110, v62, v110
	v_add_f32_e32 v110, v63, v110
	v_add_f32_e32 v32, v111, v110
	v_exp_f32_e32 v110, v33
	v_exp_f32_e32 v112, v34
	v_exp_f32_e32 v113, v35
	v_exp_f32_e32 v114, v36
	v_add_f32_e32 v32, v110, v32
	v_exp_f32_e32 v115, v37
	v_add_f32_e32 v32, v112, v32
	v_exp_f32_e32 v116, v38
	v_add_f32_e32 v32, v113, v32
	v_exp_f32_e32 v39, v39
	v_add_f32_e32 v32, v114, v32
	v_exp_f32_e32 v33, v40
	v_add_f32_e32 v32, v115, v32
	v_exp_f32_e32 v34, v41
	v_add_f32_e32 v32, v116, v32
	v_exp_f32_e32 v35, v42
	v_add_f32_e32 v32, v39, v32
	v_exp_f32_e32 v36, v43
	v_add_f32_e32 v32, v33, v32
	v_exp_f32_e32 v37, v44
	v_add_f32_e32 v32, v34, v32
	v_exp_f32_e32 v38, v45
	v_add_f32_e32 v32, v35, v32
	v_exp_f32_e32 v40, v46
	v_add_f32_e32 v32, v36, v32
	v_exp_f32_e32 v41, v47
	v_add_f32_e32 v32, v37, v32
	v_add_f32_e32 v32, v38, v32
	v_add_f32_e32 v32, v40, v32
	v_add_f32_e32 v32, v41, v32
	v_add_f32_e32 v153, v123, v32
	v_cvt_pk_bf16_f32 v32, v33, v34
	v_cvt_pk_bf16_f32 v33, v35, v36
	v_cvt_pk_bf16_f32 v34, v37, v38
	v_cvt_pk_bf16_f32 v35, v40, v41
	v_cvt_pk_bf16_f32 v36, v111, v110
	v_cvt_pk_bf16_f32 v37, v112, v113
	v_cvt_pk_bf16_f32 v38, v114, v115
	v_cvt_pk_bf16_f32 v39, v116, v39
	v_cvt_pk_bf16_f32 v40, v56, v57
	v_cvt_pk_bf16_f32 v41, v58, v59
	v_cvt_pk_bf16_f32 v42, v60, v61
	v_cvt_pk_bf16_f32 v43, v62, v63
	v_cvt_pk_bf16_f32 v44, v48, v49
	v_cvt_pk_bf16_f32 v45, v50, v51
	v_cvt_pk_bf16_f32 v46, v52, v53
	v_cvt_pk_bf16_f32 v47, v54, v55
	ds_read_b64_tr_b16 v[48:49], v108 offset:38912
	ds_read_b64_tr_b16 v[50:51], v108 offset:40448
	ds_read_b64_tr_b16 v[52:53], v108 offset:38976
	ds_read_b64_tr_b16 v[54:55], v108 offset:40512
	ds_read_b64_tr_b16 v[56:57], v108 offset:41984
	ds_read_b64_tr_b16 v[58:59], v108 offset:43520
	ds_read_b64_tr_b16 v[60:61], v108 offset:42048
	ds_read_b64_tr_b16 v[62:63], v108 offset:43584
	ds_read_b64_tr_b16 v[110:111], v108 offset:45056
	ds_read_b64_tr_b16 v[112:113], v108 offset:46592
	ds_read_b64_tr_b16 v[114:115], v108 offset:45120
	ds_read_b64_tr_b16 v[116:117], v108 offset:46656
	ds_read_b64_tr_b16 v[118:119], v108 offset:48128
	ds_read_b64_tr_b16 v[120:121], v108 offset:49664
	ds_read_b64_tr_b16 v[154:155], v108 offset:48192
	ds_read_b64_tr_b16 v[156:157], v108 offset:49728
	s_waitcnt lgkmcnt(14)
; DI f32x16 mfma32(bf16x8 a, bf16x8 b, f32x16 c) { return __builtin_amdgcn_mfma_f32_32x32x16_bf16(a, b, c, 0, 0, 0); }
; DI void attn_mla_unit(const Params& p, int b, int h, int qb, char* smem, bool pre, int nh, bool has_next) {
;     ...
;       {
;         bf16x8 kf[12];
; #pragma unroll
;         for (int s = 0; s < 6; ++s) {
;           kf[2 * s] = *(const bf16x8*)(ks + (sub * 64 + r32) * KR + (s * 16 + hh * 8) * 2);
;           kf[2 * s + 1] = *(const bf16x8*)(ks + (sub * 64 + 32 + r32) * KR + (s * 16 + hh * 8) * 2);
;         }
;         __builtin_amdgcn_sched_barrier(0); __builtin_amdgcn_s_setprio(1);
; #pragma unroll
;         for (int s = 0; s < 6; ++s) { s0 = mfma32(kf[2 * s], qf[s], s0); s1 = mfma32(kf[2 * s + 1], qf[s], s1); }
;       __builtin_amdgcn_s_setprio(0);
; }
;       float alpha; bf16x8 pf[4];
;       const bool resc = softmax_tile(s0, s1, m, l, alpha, pf, lane, (kt == 0) && (sub == 0), (sub == 0) && ((kt & 3) == 0));
;     ...
;         for (int s = 0; s < 4; ++s) { O0 = mfma32(vf[2 * s], pf[s], O0); O1 = mfma32(vf[2 * s + 1], pf[s], O1); }
;       __builtin_amdgcn_s_setprio(0);
; }
;       if (resc) { scale16(O0, alpha); scale16(O1, alpha); }
;     }
;     if (kt + 1 < 32) put_stage(smem + ((kt + 1) & 1) * STG);
;     else if (has_next) put_stage(smem);
;     __syncthreads();
;     if (kt + 2 < 32) get_stage(kt + 2);
;     else if (kt == 30 && has_next) { gk += (nh - h) * 64; gv += (nh - h) * 64; get_stage(0); }
	v_mfma_f32_32x32x16_bf16 v[16:31], v[48:51], v[44:47], v[16:31]
	s_waitcnt lgkmcnt(12)
	v_mfma_f32_32x32x16_bf16 v[0:15], v[52:55], v[44:47], v[0:15]
	s_waitcnt lgkmcnt(10)
	v_mfma_f32_32x32x16_bf16 v[16:31], v[56:59], v[40:43], v[16:31]
	s_waitcnt lgkmcnt(8)
	v_mfma_f32_32x32x16_bf16 v[0:15], v[60:63], v[40:43], v[0:15]
	s_waitcnt lgkmcnt(6)
	v_mfma_f32_32x32x16_bf16 v[16:31], v[110:113], v[36:39], v[16:31]
	s_waitcnt lgkmcnt(4)
	v_mfma_f32_32x32x16_bf16 v[0:15], v[114:117], v[36:39], v[0:15]
	s_waitcnt lgkmcnt(2)
	v_mfma_f32_32x32x16_bf16 v[16:31], v[118:121], v[32:35], v[16:31]
	s_waitcnt lgkmcnt(0)
	v_mfma_f32_32x32x16_bf16 v[0:15], v[154:157], v[32:35], v[0:15]
	v_add_u32_e32 v151, v109, v138
	v_add3_u32 v32, s48, v139, v138
	s_mov_b32 s12, 0x40000
	s_waitcnt vmcnt(4)
	ds_write_b128 v151, v[64:67] offset:51200
	s_waitcnt vmcnt(3)
	ds_write_b128 v32, v[68:71]
	s_waitcnt vmcnt(2)
	ds_write_b128 v151, v[72:75] offset:64512
	s_waitcnt vmcnt(1)
	ds_write_b128 v32, v[76:79] offset:12288
	v_add_co_u32_e32 v32, vcc, s12, v128
	v_add_u32_e32 v152, v122, v146
	s_nop 0
	v_addc_co_u32_e32 v33, vcc, 0, v129, vcc
	v_add_co_u32_e32 v34, vcc, 0x40000, v130
	s_waitcnt vmcnt(0)
	ds_write_b128 v152, v[104:107] offset:51328
	v_addc_co_u32_e32 v35, vcc, 0, v131, vcc
	s_waitcnt lgkmcnt(0)
	s_barrier
	global_load_dwordx4 v[104:107], v[32:33], off
	global_load_dwordx4 v[108:111], v[34:35], off
	v_add_co_u32_e32 v32, vcc, 0x50000, v128
	v_mov_b32_e32 v135, v145
	s_nop 0
	v_addc_co_u32_e32 v33, vcc, 0, v129, vcc
	v_add_co_u32_e32 v34, vcc, 0x50000, v130
	s_mov_b64 s[12:13], 0x70000
	s_nop 0
	v_addc_co_u32_e32 v35, vcc, 0, v131, vcc
	global_load_dwordx4 v[112:115], v[32:33], off
	global_load_dwordx4 v[116:119], v[34:35], off
	v_add_co_u32_e32 v32, vcc, 0x4000, v126
	s_mov_b32 s18, 2
	s_nop 0
	v_addc_co_u32_e32 v33, vcc, 0, v127, vcc
	global_load_dwordx4 v[120:123], v[32:33], off
	v_lshl_add_u64 v[32:33], v[132:133], 0, v[134:135]
	v_lshl_add_u64 v[64:65], s[28:29], 0, v[32:33]
	s_lshl_b64 s[14:15], s[14:15], 1
.LBB0_1482:
	s_add_i32 s19, s18, -1
	s_bitcmp1_b32 s19, 0
	s_cselect_b32 s16, 0xc800, 0
	s_add_i32 s20, s16, 0
	v_add3_u32 v67, s20, v149, v144
	ds_read_b128 v[68:71], v67
	ds_read_b128 v[72:75], v67 offset:32
	ds_read_b128 v[76:79], v67 offset:6656
	ds_read_b128 v[132:135], v67 offset:6688
	ds_read_b128 v[154:157], v67 offset:64
	ds_read_b128 v[158:161], v67 offset:96
	ds_read_b128 v[162:165], v67 offset:6720
	ds_read_b128 v[166:169], v67 offset:6752
	ds_read_b128 v[170:173], v67 offset:128
	ds_read_b128 v[174:177], v67 offset:160
	ds_read_b128 v[178:181], v67 offset:6784
	ds_read_b128 v[196:199], v67 offset:6816
	s_and_b32 s16, s19, 3
	s_waitcnt lgkmcnt(8)
	v_mfma_f32_32x32x16_bf16 v[48:63], v[68:71], v[100:103], v[220:235]
	v_mfma_f32_32x32x16_bf16 v[32:47], v[76:79], v[100:103], v[220:235]
	v_mfma_f32_32x32x16_bf16 v[48:63], v[72:75], v[96:99], v[48:63]
	v_mfma_f32_32x32x16_bf16 v[32:47], v[132:135], v[96:99], v[32:47]
	s_waitcnt lgkmcnt(4)
	v_mfma_f32_32x32x16_bf16 v[48:63], v[154:157], v[92:95], v[48:63]
	v_mfma_f32_32x32x16_bf16 v[32:47], v[162:165], v[92:95], v[32:47]
	v_mfma_f32_32x32x16_bf16 v[48:63], v[158:161], v[88:91], v[48:63]
	v_mfma_f32_32x32x16_bf16 v[32:47], v[166:169], v[88:91], v[32:47]
	s_waitcnt lgkmcnt(0)
	v_mfma_f32_32x32x16_bf16 v[48:63], v[170:173], v[84:87], v[48:63]
	v_mfma_f32_32x32x16_bf16 v[32:47], v[178:181], v[84:87], v[32:47]
	v_mfma_f32_32x32x16_bf16 v[48:63], v[174:177], v[80:83], v[48:63]
	v_mfma_f32_32x32x16_bf16 v[32:47], v[196:199], v[80:83], v[32:47]
	s_nop 9
	v_exp_f32_e32 v48, v48
	v_exp_f32_e32 v49, v49
	v_exp_f32_e32 v50, v50
	v_exp_f32_e32 v51, v51
	v_exp_f32_e32 v52, v52
	v_add_f32_e32 v66, v49, v48
	v_exp_f32_e32 v53, v53
	v_add_f32_e32 v66, v50, v66
	v_exp_f32_e32 v54, v54
	v_add_f32_e32 v66, v51, v66
	v_exp_f32_e32 v55, v55
	v_add_f32_e32 v66, v52, v66
	v_exp_f32_e32 v56, v56
	v_add_f32_e32 v66, v53, v66
	v_exp_f32_e32 v57, v57
	v_add_f32_e32 v66, v54, v66
	v_exp_f32_e32 v58, v58
	v_add_f32_e32 v66, v55, v66
	v_exp_f32_e32 v59, v59
	v_add_f32_e32 v66, v56, v66
	v_exp_f32_e32 v60, v60
	v_add_f32_e32 v66, v57, v66
	v_exp_f32_e32 v61, v61
	v_add_f32_e32 v66, v58, v66
	v_exp_f32_e32 v62, v62
	v_add_f32_e32 v66, v59, v66
	v_exp_f32_e32 v63, v63
	v_add_f32_e32 v66, v60, v66
	v_exp_f32_e32 v68, v32
	v_add_f32_e32 v66, v61, v66
	v_exp_f32_e32 v33, v33
	v_add_f32_e32 v66, v62, v66
	v_exp_f32_e32 v34, v34
	v_add_f32_e32 v66, v63, v66
	v_exp_f32_e32 v35, v35
	v_add_f32_e32 v32, v68, v66
	v_exp_f32_e32 v36, v36
	v_add_f32_e32 v32, v33, v32
	v_exp_f32_e32 v37, v37
	v_add_f32_e32 v32, v34, v32
	v_exp_f32_e32 v38, v38
	v_add_f32_e32 v32, v35, v32
	v_exp_f32_e32 v39, v39
	v_add_f32_e32 v32, v36, v32
	v_exp_f32_e32 v40, v40
	v_add_f32_e32 v32, v37, v32
	v_exp_f32_e32 v41, v41
	v_add_f32_e32 v32, v38, v32
	v_exp_f32_e32 v42, v42
	v_add_f32_e32 v32, v39, v32
	v_exp_f32_e32 v43, v43
	v_add_f32_e32 v32, v40, v32
	v_exp_f32_e32 v44, v44
	v_add_f32_e32 v32, v41, v32
	v_exp_f32_e32 v45, v45
	v_add_f32_e32 v32, v42, v32
	v_exp_f32_e32 v46, v46
	v_add_f32_e32 v32, v43, v32
	v_exp_f32_e32 v47, v47
	v_add_f32_e32 v32, v44, v32
	v_add_f32_e32 v32, v45, v32
	v_add_f32_e32 v32, v46, v32
	v_add_f32_e32 v32, v47, v32
	s_cmp_lg_u32 s16, 0
	v_add_f32_e32 v66, v153, v32
	s_cbranch_scc0 .LBB0_1484
	s_mov_b64 s[16:17], 0
	s_branch .LBB0_1487

; DI f32x16 mfma32(bf16x8 a, bf16x8 b, f32x16 c) { return __builtin_amdgcn_mfma_f32_32x32x16_bf16(a, b, c, 0, 0, 0); }
; DI void attn_mla_unit(const Params& p, int b, int h, int qb, char* smem, bool pre, int nh, bool has_next) {
;     ...
;       float alpha; bf16x8 pf[4];
;       const bool resc = softmax_tile(s0, s1, m, l, alpha, pf, lane, (kt == 0) && (sub == 0), (sub == 0) && ((kt & 3) == 0));
;       {
;         bf16x8 vf[8];
; #pragma unroll
;         for (int s = 0; s < 4; ++s) { vf[2 * s] = ld_vfrag_tr(vs, vbase, VR, sub * 64 + 16 * s, 0); vf[2 * s + 1] = ld_vfrag_tr(vs, vbase, VR, sub * 64 + 16 * s, 32); }
;         __builtin_amdgcn_sched_barrier(0); __builtin_amdgcn_s_setprio(1);
; #pragma unroll
;         for (int s = 0; s < 4; ++s) { O0 = mfma32(vf[2 * s], pf[s], O0); O1 = mfma32(vf[2 * s + 1], pf[s], O1); }
;       __builtin_amdgcn_s_setprio(0);
; }
;       if (resc) { scale16(O0, alpha); scale16(O1, alpha); }
.LBB0_1487:
	v_cvt_pk_bf16_f32 v48, v48, v49
	v_cvt_pk_bf16_f32 v49, v50, v51
	v_cvt_pk_bf16_f32 v50, v52, v53
	v_cvt_pk_bf16_f32 v52, v56, v57
	v_cvt_pk_bf16_f32 v56, v68, v33
	v_add3_u32 v68, s20, v148, v147
	v_cvt_pk_bf16_f32 v51, v54, v55
	v_cvt_pk_bf16_f32 v53, v58, v59
	v_cvt_pk_bf16_f32 v54, v60, v61
	v_cvt_pk_bf16_f32 v55, v62, v63
	v_cvt_pk_bf16_f32 v57, v34, v35
	v_cvt_pk_bf16_f32 v58, v36, v37
	v_cvt_pk_bf16_f32 v59, v38, v39
	v_cvt_pk_bf16_f32 v34, v40, v41
	v_cvt_pk_bf16_f32 v35, v42, v43
	v_cvt_pk_bf16_f32 v36, v44, v45
	ds_read_b64_tr_b16 v[38:39], v68 offset:26624
	ds_read_b64_tr_b16 v[40:41], v68 offset:28160
	ds_read_b64_tr_b16 v[42:43], v68 offset:26688
	ds_read_b64_tr_b16 v[44:45], v68 offset:28224
	ds_read_b64_tr_b16 v[60:61], v68 offset:29696
	ds_read_b64_tr_b16 v[62:63], v68 offset:31232
	ds_read_b64_tr_b16 v[70:71], v68 offset:29760
	ds_read_b64_tr_b16 v[72:73], v68 offset:31296
	ds_read_b64_tr_b16 v[74:75], v68 offset:32768
	ds_read_b64_tr_b16 v[76:77], v68 offset:34304
	ds_read_b64_tr_b16 v[132:133], v68 offset:32832
	ds_read_b64_tr_b16 v[134:135], v68 offset:34368
	ds_read_b64_tr_b16 v[154:155], v68 offset:35840
	ds_read_b64_tr_b16 v[156:157], v68 offset:37376
	ds_read_b64_tr_b16 v[158:159], v68 offset:35904
	ds_read_b64_tr_b16 v[160:161], v68 offset:37440
	v_cvt_pk_bf16_f32 v37, v46, v47
	s_waitcnt lgkmcnt(8)
	v_mfma_f32_32x32x16_bf16 v[16:31], v[38:41], v[48:51], v[16:31]
	v_mfma_f32_32x32x16_bf16 v[0:15], v[42:45], v[48:51], v[0:15]
	v_mfma_f32_32x32x16_bf16 v[16:31], v[60:63], v[52:55], v[16:31]
	v_mfma_f32_32x32x16_bf16 v[0:15], v[70:73], v[52:55], v[0:15]
	s_waitcnt lgkmcnt(0)
	v_mfma_f32_32x32x16_bf16 v[16:31], v[74:77], v[56:59], v[16:31]
	v_mfma_f32_32x32x16_bf16 v[0:15], v[132:135], v[56:59], v[0:15]
	v_mfma_f32_32x32x16_bf16 v[16:31], v[154:157], v[34:37], v[16:31]
	v_mfma_f32_32x32x16_bf16 v[0:15], v[158:161], v[34:37], v[0:15]
	s_andn2_b64 vcc, exec, s[16:17]
	s_cbranch_vccnz .LBB0_1489
	s_nop 7
	v_pk_mul_f32 v[30:31], v[32:33], v[30:31] op_sel_hi:[0,1]
	v_pk_mul_f32 v[28:29], v[32:33], v[28:29] op_sel_hi:[0,1]
	v_pk_mul_f32 v[26:27], v[32:33], v[26:27] op_sel_hi:[0,1]
	v_pk_mul_f32 v[24:25], v[32:33], v[24:25] op_sel_hi:[0,1]
	v_pk_mul_f32 v[22:23], v[32:33], v[22:23] op_sel_hi:[0,1]
	v_pk_mul_f32 v[20:21], v[32:33], v[20:21] op_sel_hi:[0,1]
	v_pk_mul_f32 v[18:19], v[32:33], v[18:19] op_sel_hi:[0,1]
	v_pk_mul_f32 v[16:17], v[32:33], v[16:17] op_sel_hi:[0,1]
	v_pk_mul_f32 v[14:15], v[32:33], v[14:15] op_sel_hi:[0,1]
	v_pk_mul_f32 v[12:13], v[32:33], v[12:13] op_sel_hi:[0,1]
	v_pk_mul_f32 v[10:11], v[32:33], v[10:11] op_sel_hi:[0,1]
	v_pk_mul_f32 v[8:9], v[32:33], v[8:9] op_sel_hi:[0,1]
	v_pk_mul_f32 v[6:7], v[32:33], v[6:7] op_sel_hi:[0,1]
	v_pk_mul_f32 v[4:5], v[32:33], v[4:5] op_sel_hi:[0,1]
	v_pk_mul_f32 v[2:3], v[32:33], v[2:3] op_sel_hi:[0,1]
	v_pk_mul_f32 v[0:1], v[32:33], v[0:1] op_sel_hi:[0,1]
; DI f32x16 mfma32(bf16x8 a, bf16x8 b, f32x16 c) { return __builtin_amdgcn_mfma_f32_32x32x16_bf16(a, b, c, 0, 0, 0); }
; DI void attn_mla_unit(const Params& p, int b, int h, int qb, char* smem, bool pre, int nh, bool has_next) {
;     ...
;   for (int kt = 0; kt < 32; ++kt) {
;     const char* ks = smem + (kt & 1) * STG; const char* vs = ks + 128 * KR;
; #pragma unroll
;     for (int sub = 0; sub < 2; ++sub) {
;       f32x16 s0, s1;
; #pragma unroll
;       for (int i = 0; i < 16; ++i) { s0[i] = -m; s1[i] = -m; }
;       {
;         bf16x8 kf[12];
; #pragma unroll
;         for (int s = 0; s < 6; ++s) {
;           kf[2 * s] = *(const bf16x8*)(ks + (sub * 64 + r32) * KR + (s * 16 + hh * 8) * 2);
;           kf[2 * s + 1] = *(const bf16x8*)(ks + (sub * 64 + 32 + r32) * KR + (s * 16 + hh * 8) * 2);
;         }
;         __builtin_amdgcn_sched_barrier(0); __builtin_amdgcn_s_setprio(1);
; #pragma unroll
;         for (int s = 0; s < 6; ++s) { s0 = mfma32(kf[2 * s], qf[s], s0); s1 = mfma32(kf[2 * s + 1], qf[s], s1); }
;       __builtin_amdgcn_s_setprio(0);
; }
;       float alpha; bf16x8 pf[4];
;       const bool resc = softmax_tile(s0, s1, m, l, alpha, pf, lane, (kt == 0) && (sub == 0), (sub == 0) && ((kt & 3) == 0));
;       {
;         bf16x8 vf[8];
; #pragma unroll
;         for (int s = 0; s < 4; ++s) { vf[2 * s] = ld_vfrag_tr(vs, vbase, VR, sub * 64 + 16 * s, 0); vf[2 * s + 1] = ld_vfrag_tr(vs, vbase, VR, sub * 64 + 16 * s, 32); }
;         __builtin_amdgcn_sched_barrier(0); __builtin_amdgcn_s_setprio(1);
; #pragma unroll
;         for (int s = 0; s < 4; ++s) { O0 = mfma32(vf[2 * s], pf[s], O0); O1 = mfma32(vf[2 * s + 1], pf[s], O1); }
;       __builtin_amdgcn_s_setprio(0);
; }
;       if (resc) { scale16(O0, alpha); scale16(O1, alpha); }
;     }
;     if (kt + 1 < 32) put_stage(smem + ((kt + 1) & 1) * STG);
;     else if (has_next) put_stage(smem);
;     __syncthreads();
;     if (kt + 2 < 32) get_stage(kt + 2);
;     else if (kt == 30 && has_next) { gk += (nh - h) * 64; gv += (nh - h) * 64; get_stage(0); }
.LBB0_1489:
	ds_read_b128 v[70:73], v67 offset:13312
	ds_read_b128 v[74:77], v67 offset:13344
	ds_read_b128 v[132:135], v67 offset:19968
	ds_read_b128 v[154:157], v67 offset:20000
	ds_read_b128 v[158:161], v67 offset:13376
	ds_read_b128 v[162:165], v67 offset:13408
	ds_read_b128 v[166:169], v67 offset:20032
	ds_read_b128 v[170:173], v67 offset:20064
	ds_read_b128 v[174:177], v67 offset:13440
	ds_read_b128 v[178:181], v67 offset:13472
	ds_read_b128 v[196:199], v67 offset:20096
	ds_read_b128 v[200:203], v67 offset:20128
	s_waitcnt lgkmcnt(8)
	v_mfma_f32_32x32x16_bf16 v[48:63], v[70:73], v[100:103], v[220:235]
	v_mfma_f32_32x32x16_bf16 v[32:47], v[132:135], v[100:103], v[220:235]
	v_mfma_f32_32x32x16_bf16 v[48:63], v[74:77], v[96:99], v[48:63]
	v_mfma_f32_32x32x16_bf16 v[32:47], v[154:157], v[96:99], v[32:47]
	s_waitcnt lgkmcnt(4)
	v_mfma_f32_32x32x16_bf16 v[48:63], v[158:161], v[92:95], v[48:63]
	v_mfma_f32_32x32x16_bf16 v[32:47], v[166:169], v[92:95], v[32:47]
	v_mfma_f32_32x32x16_bf16 v[48:63], v[162:165], v[88:91], v[48:63]
	v_mfma_f32_32x32x16_bf16 v[32:47], v[170:173], v[88:91], v[32:47]
	s_waitcnt lgkmcnt(0)
	v_mfma_f32_32x32x16_bf16 v[48:63], v[174:177], v[84:87], v[48:63]
	v_mfma_f32_32x32x16_bf16 v[32:47], v[196:199], v[84:87], v[32:47]
	v_mfma_f32_32x32x16_bf16 v[48:63], v[178:181], v[80:83], v[48:63]
	v_mfma_f32_32x32x16_bf16 v[32:47], v[200:203], v[80:83], v[32:47]
	ds_read_b64_tr_b16 v[132:133], v68 offset:38912
	ds_read_b64_tr_b16 v[134:135], v68 offset:40448
	ds_read_b64_tr_b16 v[156:157], v68 offset:40512
	ds_read_b64_tr_b16 v[154:155], v68 offset:38976
	ds_read_b64_tr_b16 v[158:159], v68 offset:41984
	ds_read_b64_tr_b16 v[160:161], v68 offset:43520
	ds_read_b64_tr_b16 v[164:165], v68 offset:43584
	ds_read_b64_tr_b16 v[162:163], v68 offset:42048
	ds_read_b64_tr_b16 v[166:167], v68 offset:45056
	ds_read_b64_tr_b16 v[168:169], v68 offset:46592
	ds_read_b64_tr_b16 v[172:173], v68 offset:46656
	ds_read_b64_tr_b16 v[170:171], v68 offset:45120
	ds_read_b64_tr_b16 v[174:175], v68 offset:48128
	ds_read_b64_tr_b16 v[176:177], v68 offset:49664
	ds_read_b64_tr_b16 v[180:181], v68 offset:49728
	ds_read_b64_tr_b16 v[178:179], v68 offset:48192
	v_exp_f32_e32 v40, v40
	v_exp_f32_e32 v41, v41
	v_exp_f32_e32 v42, v42
	v_exp_f32_e32 v43, v43
	v_exp_f32_e32 v44, v44
	v_exp_f32_e32 v45, v45
	v_exp_f32_e32 v46, v46
	v_exp_f32_e32 v47, v47
	v_exp_f32_e32 v48, v48
	v_exp_f32_e32 v49, v49
	v_exp_f32_e32 v50, v50
	v_exp_f32_e32 v51, v51
	v_exp_f32_e32 v52, v52
	v_exp_f32_e32 v53, v53
	v_exp_f32_e32 v54, v54
	v_exp_f32_e32 v55, v55
	v_exp_f32_e32 v56, v56
	v_exp_f32_e32 v57, v57
	v_exp_f32_e32 v58, v58
	v_exp_f32_e32 v59, v59
	v_exp_f32_e32 v60, v60
	v_exp_f32_e32 v61, v61
	v_exp_f32_e32 v62, v62
	v_exp_f32_e32 v63, v63
	v_exp_f32_e32 v67, v32
	v_exp_f32_e32 v69, v33
	v_exp_f32_e32 v70, v34
	v_exp_f32_e32 v71, v35
	v_exp_f32_e32 v36, v36
	v_exp_f32_e32 v37, v37
	v_exp_f32_e32 v38, v38
	v_exp_f32_e32 v39, v39
	v_cvt_pk_bf16_f32 v32, v40, v41
	v_cvt_pk_bf16_f32 v33, v42, v43
	v_cvt_pk_bf16_f32 v34, v44, v45
	v_cvt_pk_bf16_f32 v35, v46, v47
	v_cvt_pk_bf16_f32 v72, v67, v69
	v_cvt_pk_bf16_f32 v73, v70, v71
	v_cvt_pk_bf16_f32 v74, v36, v37
	v_cvt_pk_bf16_f32 v75, v38, v39
	v_cvt_pk_bf16_f32 v76, v56, v57
	v_cvt_pk_bf16_f32 v77, v58, v59
	v_cvt_pk_bf16_f32 v78, v60, v61
	v_cvt_pk_bf16_f32 v79, v62, v63
	v_cvt_pk_bf16_f32 v196, v48, v49
	v_cvt_pk_bf16_f32 v197, v50, v51
	v_cvt_pk_bf16_f32 v198, v52, v53
	v_cvt_pk_bf16_f32 v199, v54, v55
	s_waitcnt lgkmcnt(8)
	v_mfma_f32_32x32x16_bf16 v[16:31], v[132:135], v[196:199], v[16:31]
	v_mfma_f32_32x32x16_bf16 v[0:15], v[154:157], v[196:199], v[0:15]
	v_mfma_f32_32x32x16_bf16 v[16:31], v[158:161], v[76:79], v[16:31]
	v_mfma_f32_32x32x16_bf16 v[0:15], v[162:165], v[76:79], v[0:15]
	s_waitcnt lgkmcnt(0)
	v_mfma_f32_32x32x16_bf16 v[16:31], v[166:169], v[72:75], v[16:31]
	v_mfma_f32_32x32x16_bf16 v[0:15], v[170:173], v[72:75], v[0:15]
	v_mfma_f32_32x32x16_bf16 v[16:31], v[174:177], v[32:35], v[16:31]
	v_mfma_f32_32x32x16_bf16 v[0:15], v[178:181], v[32:35], v[0:15]
	s_bitcmp1_b32 s18, 0
	s_cselect_b32 s16, 0xc800, 0
	s_add_i32 s16, s16, 0
	v_add3_u32 v32, s16, v142, v138
	v_add3_u32 v33, s16, v139, v138
	s_waitcnt vmcnt(4)
	ds_write_b128 v32, v[104:107]
	s_waitcnt vmcnt(2)
	ds_write_b128 v33, v[108:111] offset:26624
	s_waitcnt vmcnt(2)
	ds_write_b128 v32, v[112:115] offset:13312
	s_waitcnt vmcnt(1)
	ds_write_b128 v33, v[116:119] offset:38912
	v_add3_u32 v32, s16, v143, v146
	s_cmp_gt_u32 s19, 29
	s_mov_b64 s[16:17], -1
	s_waitcnt vmcnt(0)
	ds_write_b128 v32, v[120:123] offset:128
	s_waitcnt lgkmcnt(0)
	s_barrier
	s_cbranch_scc0 .LBB0_1493
	s_cmp_lg_u32 s12, 0x410000
	s_cselect_b64 s[16:17], -1, 0
	s_xor_b64 s[20:21], s[10:11], -1
	s_or_b64 s[16:17], s[20:21], s[16:17]
	s_and_b64 vcc, exec, s[16:17]
	v_mov_b64_e32 v[32:33], v[128:129]
	v_mov_b64_e32 v[34:35], v[130:131]
	s_cbranch_vccnz .LBB0_1492
	v_lshl_add_u64 v[32:33], v[128:129], 0, s[14:15]
	v_add_co_u32_e32 v72, vcc, 0x10000, v32
	v_lshl_add_u64 v[34:35], v[130:131], 0, s[14:15]
	s_nop 0
	v_addc_co_u32_e32 v73, vcc, 0, v33, vcc
	global_load_dwordx4 v[104:107], v[32:33], off
	global_load_dwordx4 v[112:115], v[72:73], off
	v_add_co_u32_e32 v72, vcc, 0x10000, v34
	s_nop 1
	v_addc_co_u32_e32 v73, vcc, 0, v35, vcc
	global_load_dwordx4 v[108:111], v[34:35], off
	global_load_dwordx4 v[116:119], v[72:73], off
	global_load_dwordx4 v[120:123], v[126:127], off

; DI f32x16 mfma32(bf16x8 a, bf16x8 b, f32x16 c) { return __builtin_amdgcn_mfma_f32_32x32x16_bf16(a, b, c, 0, 0, 0); }
; DI void attn_mla_unit(const Params& p, int b, int h, int qb, char* smem, bool pre, int nh, bool has_next) {
;     ...
;     const char* ks = smem + (kt & 1) * STG; const char* vs = ks + 128 * KR;
; #pragma unroll
;     for (int sub = 0; sub < 2; ++sub) {
;       f32x16 s0, s1;
; #pragma unroll
;       for (int i = 0; i < 16; ++i) { s0[i] = -m; s1[i] = -m; }
;       {
;         bf16x8 kf[12];
; #pragma unroll
;         for (int s = 0; s < 6; ++s) {
;           kf[2 * s] = *(const bf16x8*)(ks + (sub * 64 + r32) * KR + (s * 16 + hh * 8) * 2);
;           kf[2 * s + 1] = *(const bf16x8*)(ks + (sub * 64 + 32 + r32) * KR + (s * 16 + hh * 8) * 2);
;         }
;         __builtin_amdgcn_sched_barrier(0); __builtin_amdgcn_s_setprio(1);
; #pragma unroll
;         for (int s = 0; s < 6; ++s) { s0 = mfma32(kf[2 * s], qf[s], s0); s1 = mfma32(kf[2 * s + 1], qf[s], s1); }
;       __builtin_amdgcn_s_setprio(0);
; }
;       float alpha; bf16x8 pf[4];
;       const bool resc = softmax_tile(s0, s1, m, l, alpha, pf, lane, (kt == 0) && (sub == 0), (sub == 0) && ((kt & 3) == 0));
;       {
;         bf16x8 vf[8];
; #pragma unroll
;         for (int s = 0; s < 4; ++s) { vf[2 * s] = ld_vfrag_tr(vs, vbase, VR, sub * 64 + 16 * s, 0); vf[2 * s + 1] = ld_vfrag_tr(vs, vbase, VR, sub * 64 + 16 * s, 32); }
;         __builtin_amdgcn_sched_barrier(0); __builtin_amdgcn_s_setprio(1);
; #pragma unroll
;         for (int s = 0; s < 4; ++s) { O0 = mfma32(vf[2 * s], pf[s], O0); O1 = mfma32(vf[2 * s + 1], pf[s], O1); }
;       __builtin_amdgcn_s_setprio(0);
; }
;       if (resc) { scale16(O0, alpha); scale16(O1, alpha); }
.LBB0_1497:
	v_add3_u32 v216, s48, v148, v147
	ds_read_b128 v[126:129], v141 offset:57856
	ds_read_b128 v[48:51], v141 offset:51200
	ds_read_b128 v[130:133], v141 offset:51232
	ds_read_b128 v[146:149], v141 offset:57888
	ds_read_b128 v[154:157], v141 offset:51264
	ds_read_b128 v[158:161], v141 offset:57920
	ds_read_b128 v[162:165], v141 offset:51296
	ds_read_b128 v[166:169], v141 offset:57952
	ds_read_b128 v[170:173], v141 offset:51328
	ds_read_b128 v[174:177], v141 offset:57984
	ds_read_b128 v[178:181], v141 offset:51360
	ds_read_b128 v[196:199], v141 offset:58016
	v_xor_b32_e32 v32, 0x80000000, v150
	v_mov_b32_e32 v33, v32
	v_mov_b32_e32 v34, v32
	v_mov_b32_e32 v35, v32
	v_mov_b32_e32 v36, v32
	v_mov_b32_e32 v37, v32
	v_mov_b32_e32 v38, v32
	v_mov_b32_e32 v39, v32
	v_mov_b32_e32 v40, v32
	v_mov_b32_e32 v41, v32
	v_mov_b32_e32 v42, v32
	v_mov_b32_e32 v43, v32
	v_mov_b32_e32 v44, v32
	v_mov_b32_e32 v45, v32
	v_mov_b32_e32 v46, v32
	v_mov_b32_e32 v47, v32
	s_waitcnt lgkmcnt(10)
	s_nop 0
	v_mfma_f32_32x32x16_bf16 v[64:79], v[48:51], v[100:103], v[32:47]
	v_mfma_f32_32x32x16_bf16 v[48:63], v[126:129], v[100:103], v[32:47]
	s_waitcnt lgkmcnt(9)
	v_mfma_f32_32x32x16_bf16 v[64:79], v[130:133], v[96:99], v[64:79]
	s_waitcnt lgkmcnt(8)
	v_mfma_f32_32x32x16_bf16 v[48:63], v[146:149], v[96:99], v[48:63]
	s_waitcnt lgkmcnt(7)
	v_mfma_f32_32x32x16_bf16 v[64:79], v[154:157], v[92:95], v[64:79]
	s_waitcnt lgkmcnt(6)
	v_mfma_f32_32x32x16_bf16 v[48:63], v[158:161], v[92:95], v[48:63]
	s_waitcnt lgkmcnt(5)
	v_mfma_f32_32x32x16_bf16 v[64:79], v[162:165], v[88:91], v[64:79]
	s_waitcnt lgkmcnt(4)
	v_mfma_f32_32x32x16_bf16 v[48:63], v[166:169], v[88:91], v[48:63]
	s_waitcnt lgkmcnt(3)
	v_mfma_f32_32x32x16_bf16 v[64:79], v[170:173], v[84:87], v[64:79]
	s_waitcnt lgkmcnt(2)
	v_mfma_f32_32x32x16_bf16 v[48:63], v[174:177], v[84:87], v[48:63]
	s_waitcnt lgkmcnt(1)
	v_mfma_f32_32x32x16_bf16 v[64:79], v[178:181], v[80:83], v[64:79]
	s_waitcnt lgkmcnt(0)
	v_mfma_f32_32x32x16_bf16 v[48:63], v[196:199], v[80:83], v[48:63]
	s_nop 10
	v_exp_f32_e32 v144, v60
	v_exp_f32_e32 v146, v61
	v_exp_f32_e32 v147, v62
	v_exp_f32_e32 v148, v63
	ds_read_b64_tr_b16 v[60:61], v216
	ds_read_b64_tr_b16 v[62:63], v216 offset:1536
	ds_read_b64_tr_b16 v[156:157], v216 offset:1600
	ds_read_b64_tr_b16 v[154:155], v216 offset:64
	ds_read_b64_tr_b16 v[158:159], v216 offset:3072
	ds_read_b64_tr_b16 v[160:161], v216 offset:4608
	ds_read_b64_tr_b16 v[164:165], v216 offset:4672
	ds_read_b64_tr_b16 v[162:163], v216 offset:3136
	ds_read_b64_tr_b16 v[166:167], v216 offset:6144
	ds_read_b64_tr_b16 v[168:169], v216 offset:7680
	ds_read_b64_tr_b16 v[172:173], v216 offset:7744
	ds_read_b64_tr_b16 v[170:171], v216 offset:6208
	ds_read_b64_tr_b16 v[174:175], v216 offset:9216
	ds_read_b64_tr_b16 v[176:177], v216 offset:10752
	ds_read_b64_tr_b16 v[180:181], v216 offset:10816
	ds_read_b64_tr_b16 v[178:179], v216 offset:9280
	v_exp_f32_e32 v72, v72
	v_exp_f32_e32 v73, v73
	v_exp_f32_e32 v74, v74
	v_exp_f32_e32 v75, v75
	v_exp_f32_e32 v76, v76
	v_exp_f32_e32 v77, v77
	v_exp_f32_e32 v78, v78
	v_exp_f32_e32 v79, v79
	v_exp_f32_e32 v126, v48
	v_exp_f32_e32 v127, v49
	v_exp_f32_e32 v128, v50
	v_exp_f32_e32 v129, v51
	v_exp_f32_e32 v130, v52
	v_exp_f32_e32 v131, v53
	v_exp_f32_e32 v132, v54
	v_exp_f32_e32 v133, v55
	v_exp_f32_e32 v134, v56
	v_exp_f32_e32 v135, v57
	v_exp_f32_e32 v142, v58
	v_exp_f32_e32 v143, v59
	v_exp_f32_e32 v64, v64
	v_exp_f32_e32 v65, v65
	v_exp_f32_e32 v66, v66
	v_exp_f32_e32 v67, v67
	v_exp_f32_e32 v68, v68
	v_exp_f32_e32 v69, v69
	v_exp_f32_e32 v70, v70
	v_exp_f32_e32 v71, v71
	v_cvt_pk_bf16_f32 v48, v134, v135
	v_cvt_pk_bf16_f32 v49, v142, v143
	v_cvt_pk_bf16_f32 v50, v144, v146
	v_cvt_pk_bf16_f32 v51, v147, v148
	v_cvt_pk_bf16_f32 v52, v126, v127
	v_cvt_pk_bf16_f32 v53, v128, v129
	v_cvt_pk_bf16_f32 v54, v130, v131
	v_cvt_pk_bf16_f32 v55, v132, v133
	v_cvt_pk_bf16_f32 v56, v72, v73
	v_cvt_pk_bf16_f32 v57, v74, v75
	v_cvt_pk_bf16_f32 v58, v76, v77
	v_cvt_pk_bf16_f32 v59, v78, v79
	v_cvt_pk_bf16_f32 v196, v64, v65
	v_cvt_pk_bf16_f32 v197, v66, v67
	v_cvt_pk_bf16_f32 v198, v68, v69
	v_cvt_pk_bf16_f32 v199, v70, v71
	s_waitcnt lgkmcnt(14)
	v_mfma_f32_32x32x16_bf16 v[16:31], v[60:63], v[196:199], v[16:31]
	s_waitcnt lgkmcnt(12)
	v_mfma_f32_32x32x16_bf16 v[0:15], v[154:157], v[196:199], v[0:15]
	s_waitcnt lgkmcnt(10)
	v_mfma_f32_32x32x16_bf16 v[16:31], v[158:161], v[56:59], v[16:31]
	s_waitcnt lgkmcnt(8)
	v_mfma_f32_32x32x16_bf16 v[0:15], v[162:165], v[56:59], v[0:15]
	s_waitcnt lgkmcnt(6)
	v_mfma_f32_32x32x16_bf16 v[16:31], v[166:169], v[52:55], v[16:31]
	s_waitcnt lgkmcnt(4)
	v_mfma_f32_32x32x16_bf16 v[0:15], v[170:173], v[52:55], v[0:15]
	s_waitcnt lgkmcnt(2)
	v_mfma_f32_32x32x16_bf16 v[16:31], v[174:177], v[48:51], v[16:31]
	s_waitcnt lgkmcnt(0)
; DI f32x16 mfma32(bf16x8 a, bf16x8 b, f32x16 c) { return __builtin_amdgcn_mfma_f32_32x32x16_bf16(a, b, c, 0, 0, 0); }
; DI void attn_mla_unit(const Params& p, int b, int h, int qb, char* smem, bool pre, int nh, bool has_next) {
;     ...
;     const char* ks = smem + (kt & 1) * STG; const char* vs = ks + 128 * KR;
; #pragma unroll
;     for (int sub = 0; sub < 2; ++sub) {
;       f32x16 s0, s1;
; #pragma unroll
;       for (int i = 0; i < 16; ++i) { s0[i] = -m; s1[i] = -m; }
;       {
;         bf16x8 kf[12];
; #pragma unroll
;         for (int s = 0; s < 6; ++s) {
;           kf[2 * s] = *(const bf16x8*)(ks + (sub * 64 + r32) * KR + (s * 16 + hh * 8) * 2);
;           kf[2 * s + 1] = *(const bf16x8*)(ks + (sub * 64 + 32 + r32) * KR + (s * 16 + hh * 8) * 2);
;         }
;         __builtin_amdgcn_sched_barrier(0); __builtin_amdgcn_s_setprio(1);
; #pragma unroll
;         for (int s = 0; s < 6; ++s) { s0 = mfma32(kf[2 * s], qf[s], s0); s1 = mfma32(kf[2 * s + 1], qf[s], s1); }
;       __builtin_amdgcn_s_setprio(0);
; }
;       float alpha; bf16x8 pf[4];
;       const bool resc = softmax_tile(s0, s1, m, l, alpha, pf, lane, (kt == 0) && (sub == 0), (sub == 0) && ((kt & 3) == 0));
;       {
;         bf16x8 vf[8];
; #pragma unroll
;         for (int s = 0; s < 4; ++s) { vf[2 * s] = ld_vfrag_tr(vs, vbase, VR, sub * 64 + 16 * s, 0); vf[2 * s + 1] = ld_vfrag_tr(vs, vbase, VR, sub * 64 + 16 * s, 32); }
;         __builtin_amdgcn_sched_barrier(0); __builtin_amdgcn_s_setprio(1);
; #pragma unroll
;         for (int s = 0; s < 4; ++s) { O0 = mfma32(vf[2 * s], pf[s], O0); O1 = mfma32(vf[2 * s + 1], pf[s], O1); }
;       __builtin_amdgcn_s_setprio(0);
; }
;       if (resc) { scale16(O0, alpha); scale16(O1, alpha); }
;     }
;     if (kt + 1 < 32) put_stage(smem + ((kt + 1) & 1) * STG);
;     else if (has_next) put_stage(smem);
;     __syncthreads();
;     if (kt + 2 < 32) get_stage(kt + 2);
;     else if (kt == 30 && has_next) { gk += (nh - h) * 64; gv += (nh - h) * 64; get_stage(0); }
	v_mfma_f32_32x32x16_bf16 v[0:15], v[178:181], v[48:51], v[0:15]
	v_add_u32_e32 v48, 0xfc00, v141
	ds_read_b128 v[154:157], v141 offset:64512
	ds_read_b128 v[158:161], v141 offset:64544
	ds_read_b128 v[162:165], v48 offset:6656
	ds_read_b128 v[166:169], v48 offset:6688
	ds_read_b128 v[170:173], v141 offset:64576
	ds_read_b128 v[174:177], v141 offset:64608
	ds_read_b128 v[178:181], v48 offset:6720
	ds_read_b128 v[196:199], v48 offset:6752
	ds_read_b128 v[200:203], v141 offset:64640
	ds_read_b128 v[204:207], v141 offset:64672
	ds_read_b128 v[208:211], v48 offset:6784
	ds_read_b128 v[212:215], v48 offset:6816
	s_waitcnt lgkmcnt(11)
	v_mfma_f32_32x32x16_bf16 v[48:63], v[154:157], v[100:103], v[32:47]
	s_waitcnt lgkmcnt(9)
	v_mfma_f32_32x32x16_bf16 v[32:47], v[162:165], v[100:103], v[32:47]
	v_mfma_f32_32x32x16_bf16 v[48:63], v[158:161], v[96:99], v[48:63]
	s_waitcnt lgkmcnt(8)
	v_mfma_f32_32x32x16_bf16 v[32:47], v[166:169], v[96:99], v[32:47]
	s_waitcnt lgkmcnt(7)
	v_mfma_f32_32x32x16_bf16 v[48:63], v[170:173], v[92:95], v[48:63]
	s_waitcnt lgkmcnt(5)
	v_mfma_f32_32x32x16_bf16 v[32:47], v[178:181], v[92:95], v[32:47]
	v_mfma_f32_32x32x16_bf16 v[48:63], v[174:177], v[88:91], v[48:63]
	s_waitcnt lgkmcnt(4)
	v_mfma_f32_32x32x16_bf16 v[32:47], v[196:199], v[88:91], v[32:47]
	s_waitcnt lgkmcnt(3)
	v_mfma_f32_32x32x16_bf16 v[48:63], v[200:203], v[84:87], v[48:63]
	s_waitcnt lgkmcnt(1)
	v_mfma_f32_32x32x16_bf16 v[32:47], v[208:211], v[84:87], v[32:47]
	v_mfma_f32_32x32x16_bf16 v[48:63], v[204:207], v[80:83], v[48:63]
	s_waitcnt lgkmcnt(0)
	v_mfma_f32_32x32x16_bf16 v[32:47], v[212:215], v[80:83], v[32:47]
	ds_read_b64_tr_b16 v[92:93], v216 offset:12288
	ds_read_b64_tr_b16 v[94:95], v216 offset:13824
	ds_read_b64_tr_b16 v[98:99], v216 offset:13888
	ds_read_b64_tr_b16 v[96:97], v216 offset:12352
	ds_read_b64_tr_b16 v[100:101], v216 offset:15360
	ds_read_b64_tr_b16 v[102:103], v216 offset:16896
	ds_read_b64_tr_b16 v[156:157], v216 offset:16960
	ds_read_b64_tr_b16 v[154:155], v216 offset:15424
	ds_read_b64_tr_b16 v[158:159], v216 offset:18432
	ds_read_b64_tr_b16 v[160:161], v216 offset:19968
	ds_read_b64_tr_b16 v[164:165], v216 offset:20032
	ds_read_b64_tr_b16 v[162:163], v216 offset:18496
	ds_read_b64_tr_b16 v[166:167], v216 offset:21504
	ds_read_b64_tr_b16 v[168:169], v216 offset:23040
	ds_read_b64_tr_b16 v[172:173], v216 offset:23104
	ds_read_b64_tr_b16 v[170:171], v216 offset:21568
	v_exp_f32_e32 v48, v48
	v_exp_f32_e32 v49, v49
	v_exp_f32_e32 v50, v50
	v_exp_f32_e32 v51, v51
	v_exp_f32_e32 v52, v52
	v_exp_f32_e32 v53, v53
	v_exp_f32_e32 v54, v54
	v_exp_f32_e32 v55, v55
	v_exp_f32_e32 v56, v56
	v_exp_f32_e32 v57, v57
	v_exp_f32_e32 v58, v58
	v_exp_f32_e32 v59, v59
	v_exp_f32_e32 v60, v60
	v_exp_f32_e32 v61, v61
	v_exp_f32_e32 v62, v62
	v_exp_f32_e32 v63, v63
	v_exp_f32_e32 v32, v32
	v_exp_f32_e32 v33, v33
	v_exp_f32_e32 v34, v34
	v_exp_f32_e32 v35, v35
	v_exp_f32_e32 v36, v36
	v_exp_f32_e32 v37, v37
	v_exp_f32_e32 v38, v38
	v_exp_f32_e32 v39, v39
	v_exp_f32_e32 v40, v40
	v_exp_f32_e32 v41, v41
	v_exp_f32_e32 v42, v42
	v_exp_f32_e32 v43, v43
	v_exp_f32_e32 v44, v44
	v_exp_f32_e32 v45, v45
	v_exp_f32_e32 v46, v46
	v_exp_f32_e32 v47, v47
	v_cvt_pk_bf16_f32 v80, v40, v41
	v_cvt_pk_bf16_f32 v81, v42, v43
	v_cvt_pk_bf16_f32 v82, v44, v45
	v_cvt_pk_bf16_f32 v83, v46, v47
	v_cvt_pk_bf16_f32 v84, v32, v33
	v_cvt_pk_bf16_f32 v85, v34, v35
	v_cvt_pk_bf16_f32 v86, v36, v37
	v_cvt_pk_bf16_f32 v87, v38, v39
	v_cvt_pk_bf16_f32 v88, v56, v57
	v_cvt_pk_bf16_f32 v89, v58, v59
	v_cvt_pk_bf16_f32 v90, v60, v61
	v_cvt_pk_bf16_f32 v91, v62, v63
	v_cvt_pk_bf16_f32 v174, v48, v49
	v_cvt_pk_bf16_f32 v175, v50, v51
	v_cvt_pk_bf16_f32 v176, v52, v53
	v_cvt_pk_bf16_f32 v177, v54, v55
	s_waitcnt lgkmcnt(14)
	v_mfma_f32_32x32x16_bf16 v[16:31], v[92:95], v[174:177], v[16:31]
	s_waitcnt lgkmcnt(12)
	v_mfma_f32_32x32x16_bf16 v[0:15], v[96:99], v[174:177], v[0:15]
	s_waitcnt lgkmcnt(10)
	v_mfma_f32_32x32x16_bf16 v[16:31], v[100:103], v[88:91], v[16:31]
	s_waitcnt lgkmcnt(8)
	v_mfma_f32_32x32x16_bf16 v[0:15], v[154:157], v[88:91], v[0:15]
	s_waitcnt lgkmcnt(6)
	v_mfma_f32_32x32x16_bf16 v[16:31], v[158:161], v[84:87], v[16:31]
	s_waitcnt lgkmcnt(4)
	v_mfma_f32_32x32x16_bf16 v[0:15], v[162:165], v[84:87], v[0:15]
	s_waitcnt lgkmcnt(2)
	v_mfma_f32_32x32x16_bf16 v[16:31], v[166:169], v[80:83], v[16:31]
	s_waitcnt lgkmcnt(0)
	v_mfma_f32_32x32x16_bf16 v[0:15], v[170:173], v[80:83], v[0:15]
	s_andn2_b64 vcc, exec, s[10:11]
	s_cbranch_vccnz .LBB0_1472
	v_add3_u32 v80, 0, v139, v138
	s_waitcnt vmcnt(4)
	ds_write_b128 v151, v[104:107]
	s_waitcnt vmcnt(2)
	ds_write_b128 v80, v[108:111] offset:26624
	ds_write_b128 v151, v[112:115] offset:13312
	s_waitcnt vmcnt(1)
	ds_write_b128 v80, v[116:119] offset:38912
	s_waitcnt vmcnt(0)
	ds_write_b128 v152, v[120:123] offset:128
	s_branch .LBB0_1472

; DI void attn_na_unit(const Params& p, int li, int b, int r, int hp, char* smem) {
;     ...
;   const int qbk = w & 1, hs = w >> 1, head = 2 * hp + hs;
;   const int wq = 32 * qbk + r32;
;   const int qrow = b * S_ + r * 64 + wq;
;   int cs = wq - 8; cs = cs < 0 ? 0 : (cs > 48 ? 48 : cs);
;   int rs = r - 4; rs = rs < 0 ? 0 : (rs > 56 ? 56 : rs);
;   __syncthreads();
;   for (int idx = tid; idx < 2 * 465; idx += 256) {
;     int hsel = idx >= 465 ? 1 : 0; int rem = idx - hsel * 465;
;     tab[idx] = p.ab_rpb[((size_t)(li * 8 + 2 * hp + hsel)) * 465 + rem] * LOG2E;
;   }
;   bf16x8 qf[4];
; #pragma unroll
;   for (int s = 0; s < 4; ++s) qf[s] = *(const bf16x8*)(qna + (size_t)qrow * 512 + head * 64 + s * 16 + hh * 8);
;   f32x16 O0, O1;
; #pragma unroll
;   for (int i = 0; i < 16; ++i) { O0[i] = 0.f; O1[i] = 0.f; }
;   float m = 0.f, l = 0.f;
;   const int krow = tid >> 4, kpart = tid & 15;
;   const u16* gk = kna + (size_t)(b * S_ + rs * 64 + krow) * 512 + hp * 128 + kpart * 8;
;   const u16* gv = vT + (size_t)(b * S_ + rs * 64 + krow) * 512 + hp * 128 + kpart * 8;
;   u32x4 rk[4], rv[4];
; #pragma unroll
;   for (int i = 0; i < 4; ++i) { rk[i] = *(const u32x4*)(gk + (size_t)i * 16 * 512); rv[i] = *(const u32x4*)(gv + (size_t)i * 16 * 512); }
.LBB0_1502:
	s_movk_i32 s4, 0x1d0
	v_cmp_lt_u32_e32 vcc, s4, v2
	s_movk_i32 s4, 0x744
	s_nop 0
	v_cndmask_b32_e64 v1, 0, 1, vcc
	v_or_b32_e32 v1, v1, v8
	v_cndmask_b32_e64 v11, 0, -1, vcc
	v_cndmask_b32_e32 v10, 0, v194, vcc
	v_mul_lo_u32 v144, v1, s4
	v_lshl_add_u64 v[10:11], v[2:3], 0, v[10:11]
	v_lshl_add_u64 v[12:13], s[36:37], 0, v[144:145]
	v_lshl_add_u64 v[10:11], v[10:11], 2, v[12:13]
	global_load_dword v250, v[10:11], off
	v_lshl_add_u64 v[2:3], v[2:3], 0, s[6:7]
	s_movk_i32 s4, 0x1d0
	v_cmp_lt_u32_e32 vcc, s4, v2
	s_movk_i32 s4, 0x744
	s_nop 0
	v_cndmask_b32_e64 v1, 0, 1, vcc
	v_or_b32_e32 v1, v1, v8
	v_cndmask_b32_e64 v11, 0, -1, vcc
	v_cndmask_b32_e32 v10, 0, v194, vcc
	v_mul_lo_u32 v144, v1, s4
	v_lshl_add_u64 v[10:11], v[2:3], 0, v[10:11]
	v_lshl_add_u64 v[12:13], s[36:37], 0, v[144:145]
	v_lshl_add_u64 v[10:11], v[10:11], 2, v[12:13]
	global_load_dword v251, v[10:11], off
	v_lshl_add_u64 v[2:3], v[2:3], 0, s[6:7]
	s_movk_i32 s4, 0x1d0
	v_cmp_lt_u32_e32 vcc, s4, v2
	s_movk_i32 s4, 0x744
	s_nop 0
	v_cndmask_b32_e64 v1, 0, 1, vcc
	v_or_b32_e32 v1, v1, v8
	v_cndmask_b32_e64 v11, 0, -1, vcc
	v_cndmask_b32_e32 v10, 0, v194, vcc
	v_mul_lo_u32 v144, v1, s4
	v_lshl_add_u64 v[10:11], v[2:3], 0, v[10:11]
	v_lshl_add_u64 v[12:13], s[36:37], 0, v[144:145]
	v_lshl_add_u64 v[10:11], v[10:11], 2, v[12:13]
	global_load_dword v252, v[10:11], off
	v_lshl_add_u64 v[2:3], v[2:3], 0, s[6:7]
	s_movk_i32 s4, 0x3a2
	v_cmp_gt_u32_e32 vcc, s4, v2
	s_and_saveexec_b64 s[2:3], vcc
	s_movk_i32 s4, 0x1d0
	v_cmp_lt_u32_e32 vcc, s4, v2
	s_movk_i32 s4, 0x744
	s_nop 0
	v_cndmask_b32_e64 v1, 0, 1, vcc
	v_or_b32_e32 v1, v1, v8
	v_cndmask_b32_e64 v11, 0, -1, vcc
	v_cndmask_b32_e32 v10, 0, v194, vcc
	v_mul_lo_u32 v144, v1, s4
	v_lshl_add_u64 v[10:11], v[2:3], 0, v[10:11]
	v_lshl_add_u64 v[12:13], s[36:37], 0, v[144:145]
	v_lshl_add_u64 v[10:11], v[10:11], 2, v[12:13]
	global_load_dword v253, v[10:11], off
	v_lshl_add_u64 v[2:3], v[2:3], 0, s[6:7]
	s_waitcnt vmcnt(0)
	v_mul_f32_e32 v253, 0x3fb8aa3b, v253
	ds_write_b32 v9, v253 offset:3072
	s_or_b64 exec, exec, s[2:3]
	v_mul_f32_e32 v250, 0x3fb8aa3b, v250
	v_mul_f32_e32 v251, 0x3fb8aa3b, v251
	v_mul_f32_e32 v252, 0x3fb8aa3b, v252
	ds_write_b32 v9, v250
	ds_write_b32 v9, v251 offset:1024
	ds_write_b32 v9, v252 offset:2048
	s_or_b64 exec, exec, s[2:3]
	v_readlane_b32 s2, v240, 26
	v_min_u32_e32 v2, 56, v7
	v_lshrrev_b32_e32 v49, 7, v0
	v_lshl_add_u32 v1, v36, 6, s2
	v_or_b32_e32 v112, v34, v1
	v_ashrrev_i32_e32 v113, 31, v112
	v_readlane_b32 s4, v237, 14
	v_or_b32_e32 v39, v49, v5
	v_add_u32_e32 v50, -8, v2
	v_lshlrev_b64 v[2:3], 10, v[112:113]
	v_readlane_b32 s5, v237, 15
	v_min_u32_e32 v38, 60, v6
	v_bfe_u32 v48, v35, 5, 1
	v_lshl_add_u64 v[2:3], s[4:5], 0, v[2:3]
	v_lshlrev_b32_e32 v144, 7, v39
	v_lshl_add_u64 v[2:3], v[2:3], 0, v[144:145]
	v_lshlrev_b32_e32 v32, 4, v48
	v_mov_b32_e32 v33, v145
	v_add_u32_e32 v51, -4, v38
	v_lshl_add_u64 v[2:3], v[2:3], 0, v[32:33]
	v_lshrrev_b32_e32 v33, 4, v0
	v_lshl_add_u32 v0, v51, 6, s2
	v_or_b32_e32 v144, v33, v0
	v_lshlrev_b64 v[0:1], 10, v[144:145]
	global_load_dwordx4 v[64:67], v[2:3], off
	global_load_dwordx4 v[68:71], v[2:3], off offset:32
	global_load_dwordx4 v[72:75], v[2:3], off offset:64
	global_load_dwordx4 v[76:79], v[2:3], off offset:96
	v_lshl_add_u64 v[2:3], s[28:29], 0, v[0:1]
	v_lshlrev_b32_e32 v4, 8, v4
	v_mov_b32_e32 v5, v145
	v_lshlrev_b32_e32 v6, 4, v35
	v_readlane_b32 s2, v237, 16
	v_lshl_add_u64 v[2:3], v[2:3], 0, v[4:5]
	v_and_b32_e32 v40, 0xf0, v6
	v_mov_b32_e32 v41, v145
	v_readlane_b32 s3, v237, 17
	v_lshl_add_u64 v[2:3], v[2:3], 0, v[40:41]
	v_lshlrev_b32_e32 v122, 2, v48
	v_lshl_add_u64 v[0:1], s[2:3], 0, v[0:1]
	s_movk_i32 s2, 0x4000
	v_lshl_add_u64 v[0:1], v[0:1], 0, v[4:5]
	v_add_co_u32_e32 v12, vcc, s2, v2
	v_lshl_add_u64 v[0:1], v[0:1], 0, v[40:41]
	s_nop 0
	v_addc_co_u32_e32 v13, vcc, 0, v3, vcc
	v_add_co_u32_e32 v16, vcc, s2, v0
	s_mov_b32 s2, 0x8000
	s_nop 0
	v_addc_co_u32_e32 v17, vcc, 0, v1, vcc
	v_add_co_u32_e32 v20, vcc, s2, v2
	global_load_dwordx4 v[4:7], v[2:3], off
	global_load_dwordx4 v[8:11], v[0:1], off
	v_addc_co_u32_e32 v21, vcc, 0, v3, vcc
	v_add_co_u32_e32 v24, vcc, s2, v0
	global_load_dwordx4 v[12:15], v[12:13], off
	s_nop 0
	v_addc_co_u32_e32 v25, vcc, 0, v1, vcc
	s_mov_b32 s2, 0xc000
	global_load_dwordx4 v[16:19], v[16:17], off
	v_add_co_u32_e32 v28, vcc, s2, v2
	global_load_dwordx4 v[20:23], v[20:21], off
	s_nop 0
	v_addc_co_u32_e32 v29, vcc, 0, v3, vcc
	global_load_dwordx4 v[24:27], v[24:25], off
	v_add_co_u32_e32 v42, vcc, s2, v0
	global_load_dwordx4 v[28:31], v[28:29], off
	s_nop 0
	v_addc_co_u32_e32 v43, vcc, 0, v1, vcc
	global_load_dwordx4 v[44:47], v[42:43], off
	v_add_u32_e32 v40, v117, v40
	s_movk_i32 s2, 0x110
	v_mad_u32_u24 v43, v37, s2, v117
	v_mad_u32_u24 v48, v33, s2, v40
	s_movk_i32 s2, 0x140
	s_waitcnt lgkmcnt(0)
	s_barrier
; DI f32x16 mfma32(bf16x8 a, bf16x8 b, f32x16 c) { return __builtin_amdgcn_mfma_f32_32x32x16_bf16(a, b, c, 0, 0, 0); }
; DI void attn_na_unit(const Params& p, int li, int b, int r, int hp, char* smem) {
;     ...
;   for (int kt = 0; kt < 8; ++kt) {
;     __syncthreads();
; #pragma unroll
;     for (int i = 0; i < 4; ++i) {
;       *(u32x4*)(ks + (krow + 16 * i) * KR + kpart * 16) = rk[i];
;       *(u32x4*)(vs + (krow + 16 * i) * VR + kpart * 16) = rv[i];
;     }
;     __syncthreads();
;     if (kt + 1 < 8) {
;       const int k0 = (kt + 1) * 64;
; #pragma unroll
;       for (int i = 0; i < 4; ++i) { rk[i] = *(const u32x4*)(gk + (size_t)(k0 + i * 16) * 512); rv[i] = *(const u32x4*)(gv + (size_t)(k0 + i * 16) * 512); }
;     }
;     f32x16 s0, s1;
; #pragma unroll
;     for (int i = 0; i < 16; ++i) { s0[i] = -m; s1[i] = -m; }
;     {
;       bf16x8 kf[8];
; #pragma unroll
;       for (int s = 0; s < 4; ++s) {
;         kf[2 * s] = *(const bf16x8*)(ks + r32 * KR + (hs * 64 + s * 16 + hh * 8) * 2);
;         kf[2 * s + 1] = *(const bf16x8*)(ks + (32 + r32) * KR + (hs * 64 + s * 16 + hh * 8) * 2);
;       }
;       __builtin_amdgcn_sched_barrier(0); __builtin_amdgcn_s_setprio(1);
; #pragma unroll
;       for (int s = 0; s < 4; ++s) { s0 = mfma32(kf[2 * s], qf[s], s0); s1 = mfma32(kf[2 * s + 1], qf[s], s1); }
;     __builtin_amdgcn_s_setprio(0);
; }
	v_and_b32_e32 v42, 0x80, v35
	v_or_b32_e32 v52, v32, v42
	v_add_u32_e32 v123, v43, v52
	v_mul_u32_u24_e32 v41, 0x744, v49
	v_sub_u32_e32 v51, v51, v36
	s_waitcnt vmcnt(7)
	ds_write_b128 v48, v[4:7]
	v_mad_u32_u24 v4, v33, s2, v40
	s_mov_b32 s2, 0x10000
	s_waitcnt vmcnt(6)
	ds_write_b128 v4, v[8:11] offset:17408
	s_waitcnt vmcnt(5)
	ds_write_b128 v48, v[12:15] offset:4352
	s_waitcnt vmcnt(4)
	ds_write_b128 v4, v[16:19] offset:22528
	s_waitcnt vmcnt(3)
	ds_write_b128 v48, v[20:23] offset:8704
	s_waitcnt vmcnt(2)
	ds_write_b128 v4, v[24:27] offset:27648
	s_waitcnt vmcnt(1)
	ds_write_b128 v48, v[28:31] offset:13056
	s_waitcnt vmcnt(0)
	ds_write_b128 v4, v[44:47] offset:32768
	v_add_co_u32_e32 v4, vcc, s2, v2
	s_waitcnt lgkmcnt(0)
	s_nop 0
	v_addc_co_u32_e32 v5, vcc, 0, v3, vcc
	s_barrier
	global_load_dwordx4 v[80:83], v[4:5], off
	v_add_co_u32_e32 v4, vcc, s2, v0
	s_mov_b32 s2, 0x14000
	s_nop 0
	v_addc_co_u32_e32 v5, vcc, 0, v1, vcc
	global_load_dwordx4 v[84:87], v[4:5], off
	v_add_co_u32_e32 v4, vcc, s2, v2
	s_nop 1
	v_addc_co_u32_e32 v5, vcc, 0, v3, vcc
	global_load_dwordx4 v[88:91], v[4:5], off
	v_add_co_u32_e32 v4, vcc, s2, v0
	s_mov_b32 s2, 0x18000
	s_nop 0
	v_addc_co_u32_e32 v5, vcc, 0, v1, vcc
	global_load_dwordx4 v[92:95], v[4:5], off
	v_add_co_u32_e32 v4, vcc, s2, v2
	s_nop 1
	v_addc_co_u32_e32 v5, vcc, 0, v3, vcc
	global_load_dwordx4 v[96:99], v[4:5], off
	v_add_co_u32_e32 v4, vcc, s2, v0
	s_mov_b32 s2, 0x1c000
	s_nop 0
	v_addc_co_u32_e32 v5, vcc, 0, v1, vcc
	v_add_co_u32_e32 v2, vcc, s2, v2
	global_load_dwordx4 v[100:103], v[4:5], off
	s_nop 0
	v_addc_co_u32_e32 v3, vcc, 0, v3, vcc
	v_add_co_u32_e32 v0, vcc, s2, v0
	global_load_dwordx4 v[104:107], v[2:3], off
	s_nop 0
	v_addc_co_u32_e32 v1, vcc, 0, v1, vcc
	global_load_dwordx4 v[108:111], v[0:1], off
	ds_read_b128 v[44:47], v123 offset:8704
	ds_read_b128 v[52:55], v123
	ds_read_b128 v[56:59], v123 offset:32
	ds_read_b128 v[60:63], v123 offset:8736
	ds_read_b128 v[124:127], v123 offset:64
	ds_read_b128 v[128:131], v123 offset:8768
	ds_read_b128 v[132:135], v123 offset:96
	ds_read_b128 v[136:139], v123 offset:8800
	s_mov_b32 s9, s8
	s_mov_b32 s10, s8
	s_mov_b32 s11, s8
	s_mov_b32 s12, s8
	s_mov_b32 s13, s8
	s_mov_b32 s14, s8
	s_mov_b32 s15, s8
	s_mov_b32 s16, s8
	s_mov_b32 s17, s8
	s_mov_b32 s18, s8
	s_mov_b32 s19, s8
	s_mov_b32 s20, s8
	s_mov_b32 s21, s8
	s_mov_b32 s22, s8
	s_mov_b32 s23, s8
	v_mov_b64_e32 v[0:1], s[8:9]
	v_mov_b64_e32 v[2:3], s[10:11]
	v_mov_b64_e32 v[4:5], s[12:13]
	v_mov_b64_e32 v[6:7], s[14:15]
	v_mov_b64_e32 v[8:9], s[16:17]
	v_mov_b64_e32 v[10:11], s[18:19]
	v_mov_b64_e32 v[12:13], s[20:21]
	v_mov_b64_e32 v[14:15], s[22:23]
	s_waitcnt lgkmcnt(6)
	s_nop 0
	v_mfma_f32_32x32x16_bf16 v[16:31], v[52:55], v[64:67], v[0:15]
	v_mfma_f32_32x32x16_bf16 v[0:15], v[44:47], v[64:67], v[0:15]
	s_waitcnt lgkmcnt(5)
	v_mfma_f32_32x32x16_bf16 v[16:31], v[56:59], v[68:71], v[16:31]
	s_waitcnt lgkmcnt(4)
	v_mfma_f32_32x32x16_bf16 v[0:15], v[60:63], v[68:71], v[0:15]
	s_waitcnt lgkmcnt(3)
	v_mfma_f32_32x32x16_bf16 v[16:31], v[124:127], v[72:75], v[16:31]
	s_waitcnt lgkmcnt(2)
	v_mfma_f32_32x32x16_bf16 v[0:15], v[128:131], v[72:75], v[0:15]
	s_waitcnt lgkmcnt(1)
	v_mfma_f32_32x32x16_bf16 v[16:31], v[132:135], v[76:79], v[16:31]
	s_waitcnt lgkmcnt(0)
	v_mfma_f32_32x32x16_bf16 v[0:15], v[136:139], v[76:79], v[0:15]
	s_movk_i32 s2, 0x7c
	v_mul_lo_u32 v43, v51, s2
	v_add3_u32 v63, v117, v41, v43
	v_or_b32_e32 v43, 32, v122
	v_sub_u32_e32 v44, v122, v50
	v_cmp_gt_u32_e64 s[76:77], 16, v44
	v_sub_u32_e32 v44, v43, v50
	v_sub_u32_e32 v43, v43, v34
	v_add_u32_e32 v43, 15, v43
	v_cmp_gt_u32_e64 s[78:79], 16, v44
	v_mov_b32_e32 v60, 0xf149f2ca
	v_mov_b32_e32 v61, 0xf149f2ca
	v_cndmask_b32_e64 v43, 0, v43, s[78:79]
	v_lshl_add_u32 v44, v43, 2, v63
	ds_read_b32 v62, v44 offset:38756
	v_sub_u32_e32 v44, v122, v34
	v_lshl_add_u32 v114, v44, 2, v63
	s_and_saveexec_b64 s[2:3], s[76:77]
	s_cbranch_execz .LBB0_1505
	ds_read_b32 v44, v114 offset:38816
	s_waitcnt lgkmcnt(0)
	v_add_f32_e32 v61, v16, v44

; DI bool softmax_tile(f32x16& s0, f32x16& s1, float& m, float& l, float& alpha, bf16x8* pf, int lane, bool first, bool check) {
;   if (first) {
;     float mx = fmaxf(s0[0], s1[0]);
; #pragma unroll
;     for (int i = 1; i < 16; ++i) mx = fmaxf(mx, fmaxf(s0[i], s1[i]));
;     mx = fmaxf(mx, shx(mx, 32, lane));
;     m += mx;
; #pragma unroll
;     for (int i = 0; i < 16; ++i) { s0[i] -= mx; s1[i] -= mx; }
;   }
;   float sum = 0.f;
; #pragma unroll
;   for (int i = 0; i < 16; ++i) { s0[i] = __builtin_amdgcn_exp2f(s0[i]); sum += s0[i]; }
; #pragma unroll
;   for (int i = 0; i < 16; ++i) { s1[i] = __builtin_amdgcn_exp2f(s1[i]); sum += s1[i]; }
;   l += sum;
;   pf[0] = pack8(s0, 0); pf[1] = pack8(s0, 8); pf[2] = pack8(s1, 0); pf[3] = pack8(s1, 8);
; DI void attn_na_unit(const Params& p, int li, int b, int r, int hp, char* smem) {
;     ...
;     const int drow = rs + kt - r + 7;
;     const float* trow = tab + hs * 465 + drow * 31;
; #pragma unroll
;     for (int i = 0; i < 16; ++i) {
;       const int kc0 = (i & 3) + 8 * (i >> 2) + 4 * hh;
;       const int kc1 = kc0 + 32;
;       const bool v0 = (unsigned)(kc0 - cs) < 16u;
;       const bool v1 = (unsigned)(kc1 - cs) < 16u;
;       const int d0 = v0 ? (kc0 - wq + 15) : 0;
;       const int d1 = v1 ? (kc1 - wq + 15) : 0;
;       const float b0 = trow[d0], b1 = trow[d1];
;       s0[i] = v0 ? s0[i] + b0 : -1e30f;
;       s1[i] = v1 ? s1[i] + b1 : -1e30f;
;     }
;     float alpha; bf16x8 pf[4];
;     const bool resc = softmax_tile(s0, s1, m, l, alpha, pf, lane, kt == 0, true);
.LBB0_1535:
	s_or_b64 exec, exec, s[6:7]
	v_and_b32_e32 v31, 63, v35
	v_bfe_u32 v34, v35, 2, 2
	v_lshrrev_b32_e32 v50, 3, v35
	v_and_or_b32 v34, v50, 4, v34
	v_and_b32_e32 v50, 16, v35
	v_lshlrev_b32_e32 v31, 2, v31
	s_waitcnt lgkmcnt(14)
	v_add_f32_e32 v1, v1, v115
	v_and_or_b32 v50, v31, 12, v50
	v_mul_u32_u24_e32 v34, 0x140, v34
	s_waitcnt lgkmcnt(12)
	v_add_f32_e32 v3, v3, v125
	v_add_f32_e32 v2, v2, v124
	v_cndmask_b32_e64 v1, v195, v1, s[92:93]
	v_add_f32_e32 v0, v0, v62
	v_lshlrev_b32_e32 v50, 1, v50
	s_waitcnt lgkmcnt(0)
	v_add_f32_e32 v15, v15, v30
	v_max_f32_e32 v30, v60, v60
	v_cndmask_b32_e64 v3, v195, v3, s[72:73]
	v_cndmask_b32_e64 v2, v195, v2, s[94:95]
	v_cndmask_b32_e64 v0, v195, v0, s[78:79]
	v_xor_b32_e32 v124, 0x80, v31
	v_add3_u32 v31, v117, v50, v34
	v_max_f32_e32 v30, v30, v1
	v_max_f32_e32 v34, v17, v17
	v_max_f32_e32 v50, v16, v16
	v_add_f32_e32 v5, v5, v127
	v_add_f32_e32 v4, v4, v126
	v_max3_f32 v30, v61, v0, v30
	v_max_f32_e32 v34, v34, v2
	v_max_f32_e32 v50, v50, v3
	v_cndmask_b32_e64 v5, v195, v5, s[74:75]
	v_cndmask_b32_e64 v4, v195, v4, s[80:81]
	v_max3_f32 v30, v30, v34, v50
	v_max_f32_e32 v34, v19, v19
	v_max_f32_e32 v50, v18, v18
	v_add_f32_e32 v7, v7, v129
	v_add_f32_e32 v6, v6, v128
	v_max_f32_e32 v34, v34, v4
	v_max_f32_e32 v50, v50, v5
	v_cndmask_b32_e64 v7, v195, v7, s[48:49]
	v_cndmask_b32_e64 v6, v195, v6, s[58:59]
	v_max3_f32 v30, v30, v34, v50
	v_max_f32_e32 v34, v21, v21
	v_max_f32_e32 v50, v20, v20
	v_add_f32_e32 v9, v9, v131
	v_add_f32_e32 v8, v8, v130
	v_max_f32_e32 v34, v34, v6
	v_max_f32_e32 v50, v50, v7
	v_cndmask_b32_e64 v9, v195, v9, s[62:63]
	v_cndmask_b32_e64 v8, v195, v8, s[50:51]
	v_max3_f32 v30, v30, v34, v50
	v_max_f32_e32 v34, v23, v23
	v_max_f32_e32 v50, v22, v22
	v_add_f32_e32 v11, v11, v133
	v_add_f32_e32 v10, v10, v132
	v_max_f32_e32 v34, v34, v8
	v_max_f32_e32 v50, v50, v9
	v_cndmask_b32_e64 v11, v195, v11, s[44:45]
	v_cndmask_b32_e64 v10, v195, v10, s[38:39]
	v_max3_f32 v30, v30, v34, v50
	v_max_f32_e32 v34, v25, v25
	v_max_f32_e32 v50, v24, v24
	v_add_f32_e32 v13, v13, v135
	v_add_f32_e32 v12, v12, v134
	v_max_f32_e32 v34, v34, v10
	v_max_f32_e32 v50, v50, v11
	v_cndmask_b32_e64 v13, v195, v13, s[82:83]
	v_cndmask_b32_e64 v12, v195, v12, s[56:57]
	v_max3_f32 v30, v30, v34, v50
	v_max_f32_e32 v34, v27, v27
	v_max_f32_e32 v50, v26, v26
	v_add_f32_e32 v14, v14, v136
	v_max_f32_e32 v34, v34, v12
	v_max_f32_e32 v50, v50, v13
	v_cndmask_b32_e64 v14, v195, v14, s[84:85]
	v_cndmask_b32_e64 v15, v195, v15, s[2:3]
	v_max3_f32 v30, v30, v34, v50
	v_max_f32_e32 v34, v28, v28
	v_max_f32_e32 v50, v29, v29
	v_max_f32_e32 v34, v34, v14
	v_max_f32_e32 v50, v50, v15
	v_max3_f32 v30, v30, v34, v50
	ds_bpermute_b32 v34, v124, v30
	v_add_u32_e32 v125, v31, v42
	s_waitcnt lgkmcnt(0)
	v_max_f32_e32 v34, v34, v34
	v_max_f32_e32 v50, v30, v34
	v_sub_f32_e32 v30, v61, v50
	v_sub_f32_e32 v34, v60, v50
	v_exp_f32_e32 v30, v30
	v_sub_f32_e32 v17, v17, v50
	v_exp_f32_e32 v34, v34
	v_sub_f32_e32 v16, v16, v50
	v_exp_f32_e32 v17, v17
	v_sub_f32_e32 v19, v19, v50
	v_exp_f32_e32 v16, v16
	v_sub_f32_e32 v18, v18, v50
	v_add_f32_e32 v60, 0, v30
	v_exp_f32_e32 v19, v19
	v_sub_f32_e32 v21, v21, v50
	v_add_f32_e32 v60, v34, v60
	v_exp_f32_e32 v18, v18
	v_sub_f32_e32 v20, v20, v50
	v_add_f32_e32 v60, v17, v60
	v_exp_f32_e32 v21, v21
	v_sub_f32_e32 v23, v23, v50
	v_add_f32_e32 v60, v16, v60
	v_exp_f32_e32 v20, v20
	v_sub_f32_e32 v22, v22, v50
	v_add_f32_e32 v60, v19, v60
	v_exp_f32_e32 v23, v23
	v_sub_f32_e32 v25, v25, v50
	v_add_f32_e32 v60, v18, v60
	v_exp_f32_e32 v22, v22
	v_sub_f32_e32 v24, v24, v50
	v_add_f32_e32 v60, v21, v60
	v_exp_f32_e32 v25, v25
	v_sub_f32_e32 v27, v27, v50
	v_add_f32_e32 v60, v20, v60
	v_exp_f32_e32 v24, v24
	v_sub_f32_e32 v26, v26, v50
	v_add_f32_e32 v60, v23, v60
	v_exp_f32_e32 v27, v27
	v_sub_f32_e32 v28, v28, v50
	v_add_f32_e32 v60, v22, v60
	v_exp_f32_e32 v26, v26
	v_sub_f32_e32 v29, v29, v50
	v_add_f32_e32 v60, v25, v60
	v_exp_f32_e32 v28, v28
	v_sub_f32_e32 v0, v0, v50
	v_add_f32_e32 v60, v24, v60
	v_exp_f32_e32 v29, v29
	v_sub_f32_e32 v1, v1, v50
	v_add_f32_e32 v60, v27, v60
	v_exp_f32_e32 v61, v0
	v_sub_f32_e32 v2, v2, v50
	v_add_f32_e32 v60, v26, v60
	v_exp_f32_e32 v62, v1
	v_sub_f32_e32 v3, v3, v50
	v_add_f32_e32 v60, v28, v60
	v_exp_f32_e32 v63, v2
	v_sub_f32_e32 v4, v4, v50
	v_add_f32_e32 v60, v29, v60
	v_exp_f32_e32 v114, v3
	v_sub_f32_e32 v5, v5, v50
	v_add_f32_e32 v0, v61, v60
	v_exp_f32_e32 v4, v4
	v_sub_f32_e32 v6, v6, v50
	v_add_f32_e32 v0, v62, v0
	v_exp_f32_e32 v5, v5
	v_sub_f32_e32 v7, v7, v50
	v_add_f32_e32 v0, v63, v0
	v_exp_f32_e32 v6, v6
	v_sub_f32_e32 v8, v8, v50
	v_add_f32_e32 v0, v114, v0
	v_exp_f32_e32 v7, v7
	v_sub_f32_e32 v9, v9, v50
	v_add_f32_e32 v0, v4, v0
	v_exp_f32_e32 v8, v8
	v_sub_f32_e32 v10, v10, v50
	v_add_f32_e32 v0, v5, v0
	v_exp_f32_e32 v9, v9
	v_sub_f32_e32 v11, v11, v50
	v_add_f32_e32 v0, v6, v0
	v_exp_f32_e32 v10, v10
	v_sub_f32_e32 v12, v12, v50
	v_add_f32_e32 v0, v7, v0
	v_exp_f32_e32 v11, v11
	v_sub_f32_e32 v13, v13, v50
	v_add_f32_e32 v0, v8, v0
	v_exp_f32_e32 v12, v12
	v_sub_f32_e32 v14, v14, v50
	v_add_f32_e32 v0, v9, v0
	v_exp_f32_e32 v13, v13
	v_sub_f32_e32 v15, v15, v50
	v_add_f32_e32 v0, v10, v0
	v_exp_f32_e32 v14, v14
	v_add_f32_e32 v0, v11, v0
	v_exp_f32_e32 v15, v15
	v_add_f32_e32 v0, v12, v0
	v_add_f32_e32 v0, v13, v0
	v_add_f32_e32 v0, v14, v0
	v_add_f32_e32 v60, v15, v0
	v_cvt_pk_bf16_f32 v132, v4, v5
	ds_bpermute_b32 v4, v124, v60
	v_cvt_pk_bf16_f32 v130, v61, v62
	v_cvt_pk_bf16_f32 v133, v6, v7
	v_cvt_pk_bf16_f32 v134, v8, v9
	v_cvt_pk_bf16_f32 v135, v10, v11
	s_waitcnt lgkmcnt(0)
; DI f32x16 mfma32(bf16x8 a, bf16x8 b, f32x16 c) { return __builtin_amdgcn_mfma_f32_32x32x16_bf16(a, b, c, 0, 0, 0); }
; DI bool softmax_tile(f32x16& s0, f32x16& s1, float& m, float& l, float& alpha, bf16x8* pf, int lane, bool first, bool check) {
;     ...
;   alpha = 1.f;
;   if (!check) return false;
;   const float rsum = sum + shx(sum, 32, lane);
;   const bool trig = rsum > 65536.f;
;   const bool resc = (__builtin_amdgcn_ballot_w64(trig) != 0ull);
;   alpha = 1.f;
;   if (resc) {
;     const float d = trig ? (float)(__builtin_amdgcn_frexp_expf(rsum) - 7) : 0.f;
;     alpha = __builtin_amdgcn_exp2f(-d);
;     m += d; l *= alpha;
;   }
;   return resc;
; DI void attn_na_unit(const Params& p, int li, int b, int r, int hp, char* smem) {
;     ...
;     {
;       bf16x8 vf[8];
; #pragma unroll
;       for (int s = 0; s < 4; ++s) { vf[2 * s] = ld_vfrag_tr(vs, vbase, VR, 16 * s, hs * 64); vf[2 * s + 1] = ld_vfrag_tr(vs, vbase, VR, 16 * s, hs * 64 + 32); }
;       __builtin_amdgcn_sched_barrier(0); __builtin_amdgcn_s_setprio(1);
; #pragma unroll
;       for (int s = 0; s < 4; ++s) { O0 = mfma32(vf[2 * s], pf[s], O0); O1 = mfma32(vf[2 * s + 1], pf[s], O1); }
;     __builtin_amdgcn_s_setprio(0);
; }
;     if (resc) { scale16(O0, alpha); scale16(O1, alpha); }
	v_add_f32_e32 v4, v60, v4
	v_cmp_lt_f32_e32 vcc, s88, v4
	v_frexp_exp_i32_f32_e32 v4, v4
	v_add_u32_e32 v4, -7, v4
	v_cvt_f32_i32_e32 v4, v4
	v_cvt_pk_bf16_f32 v0, v30, v34
	s_cmp_eq_u64 vcc, 0
	v_cvt_pk_bf16_f32 v1, v17, v16
	v_cndmask_b32_e32 v61, 0, v4, vcc
	ds_read_b64_tr_b16 v[4:5], v125 offset:17408
	ds_read_b64_tr_b16 v[6:7], v125 offset:19968
	ds_read_b64_tr_b16 v[8:9], v125 offset:17472
	ds_read_b64_tr_b16 v[10:11], v125 offset:20032
	ds_read_b64_tr_b16 v[138:139], v125 offset:22528
	ds_read_b64_tr_b16 v[140:141], v125 offset:25088
	ds_read_b64_tr_b16 v[146:147], v125 offset:22592
	ds_read_b64_tr_b16 v[148:149], v125 offset:25152
	ds_read_b64_tr_b16 v[150:151], v125 offset:27648
	ds_read_b64_tr_b16 v[152:153], v125 offset:30208
	ds_read_b64_tr_b16 v[154:155], v125 offset:27712
	ds_read_b64_tr_b16 v[156:157], v125 offset:30272
	ds_read_b64_tr_b16 v[158:159], v125 offset:32768
	ds_read_b64_tr_b16 v[160:161], v125 offset:35328
	ds_read_b64_tr_b16 v[162:163], v125 offset:32832
	ds_read_b64_tr_b16 v[164:165], v125 offset:35392
	v_exp_f32_e64 v34, -v61
	v_cvt_pk_bf16_f32 v2, v19, v18
	v_cvt_pk_bf16_f32 v3, v21, v20
	s_cselect_b64 s[6:7], -1, 0
	v_cvt_pk_bf16_f32 v126, v23, v22
	v_cvt_pk_bf16_f32 v127, v25, v24
	v_cvt_pk_bf16_f32 v128, v27, v26
	v_cvt_pk_bf16_f32 v129, v28, v29
	v_cvt_pk_bf16_f32 v131, v63, v114
	v_cvt_pk_bf16_f32 v136, v12, v13
	v_cvt_pk_bf16_f32 v137, v14, v15
	s_waitcnt lgkmcnt(14)
	v_mfma_f32_32x32x16_bf16 v[16:31], v[4:7], v[0:3], 0
	s_waitcnt lgkmcnt(12)
	v_mfma_f32_32x32x16_bf16 v[0:15], v[8:11], v[0:3], 0
	s_waitcnt lgkmcnt(10)
	v_mfma_f32_32x32x16_bf16 v[16:31], v[138:141], v[126:129], v[16:31]
	s_waitcnt lgkmcnt(8)
	v_mfma_f32_32x32x16_bf16 v[0:15], v[146:149], v[126:129], v[0:15]
	s_waitcnt lgkmcnt(6)
	v_mfma_f32_32x32x16_bf16 v[16:31], v[150:153], v[130:133], v[16:31]
	s_waitcnt lgkmcnt(4)
	v_mfma_f32_32x32x16_bf16 v[0:15], v[154:157], v[130:133], v[0:15]
	s_waitcnt lgkmcnt(2)
	v_mfma_f32_32x32x16_bf16 v[16:31], v[158:161], v[134:137], v[16:31]
	s_waitcnt lgkmcnt(0)
	v_mfma_f32_32x32x16_bf16 v[0:15], v[162:165], v[134:137], v[0:15]
	s_cbranch_vccz .LBB0_1537
	s_nop 7
	v_pk_mul_f32 v[30:31], v[30:31], v[34:35] op_sel_hi:[1,0]
	v_pk_mul_f32 v[28:29], v[28:29], v[34:35] op_sel_hi:[1,0]
	v_pk_mul_f32 v[26:27], v[26:27], v[34:35] op_sel_hi:[1,0]
	v_pk_mul_f32 v[24:25], v[24:25], v[34:35] op_sel_hi:[1,0]
	v_pk_mul_f32 v[22:23], v[22:23], v[34:35] op_sel_hi:[1,0]
	v_pk_mul_f32 v[20:21], v[20:21], v[34:35] op_sel_hi:[1,0]
	v_pk_mul_f32 v[18:19], v[18:19], v[34:35] op_sel_hi:[1,0]
	v_pk_mul_f32 v[16:17], v[16:17], v[34:35] op_sel_hi:[1,0]
	v_pk_mul_f32 v[14:15], v[14:15], v[34:35] op_sel_hi:[1,0]
	v_pk_mul_f32 v[12:13], v[12:13], v[34:35] op_sel_hi:[1,0]
	v_pk_mul_f32 v[10:11], v[10:11], v[34:35] op_sel_hi:[1,0]
	v_pk_mul_f32 v[8:9], v[8:9], v[34:35] op_sel_hi:[1,0]
	v_pk_mul_f32 v[6:7], v[6:7], v[34:35] op_sel_hi:[1,0]
	v_pk_mul_f32 v[4:5], v[4:5], v[34:35] op_sel_hi:[1,0]
	v_pk_mul_f32 v[2:3], v[2:3], v[34:35] op_sel_hi:[1,0]
	v_pk_mul_f32 v[0:1], v[0:1], v[34:35] op_sel_hi:[1,0]

; DI f32x16 mfma32(bf16x8 a, bf16x8 b, f32x16 c) { return __builtin_amdgcn_mfma_f32_32x32x16_bf16(a, b, c, 0, 0, 0); }
; DI void attn_na_unit(const Params& p, int li, int b, int r, int hp, char* smem) {
;     ...
;     f32x16 s0, s1;
; #pragma unroll
;     for (int i = 0; i < 16; ++i) { s0[i] = -m; s1[i] = -m; }
;     {
;       bf16x8 kf[8];
; #pragma unroll
;       for (int s = 0; s < 4; ++s) {
;         kf[2 * s] = *(const bf16x8*)(ks + r32 * KR + (hs * 64 + s * 16 + hh * 8) * 2);
;         kf[2 * s + 1] = *(const bf16x8*)(ks + (32 + r32) * KR + (hs * 64 + s * 16 + hh * 8) * 2);
;       }
;       __builtin_amdgcn_sched_barrier(0); __builtin_amdgcn_s_setprio(1);
; #pragma unroll
;       for (int s = 0; s < 4; ++s) { s0 = mfma32(kf[2 * s], qf[s], s0); s1 = mfma32(kf[2 * s + 1], qf[s], s1); }
;     __builtin_amdgcn_s_setprio(0);
; }
;     const int drow = rs + kt - r + 7;
;     const float* trow = tab + hs * 465 + drow * 31;
; #pragma unroll
;     for (int i = 0; i < 16; ++i) {
;       const int kc0 = (i & 3) + 8 * (i >> 2) + 4 * hh;
;       const int kc1 = kc0 + 32;
;       const bool v0 = (unsigned)(kc0 - cs) < 16u;
;       const bool v1 = (unsigned)(kc1 - cs) < 16u;
;       const int d0 = v0 ? (kc0 - wq + 15) : 0;
;       const int d1 = v1 ? (kc1 - wq + 15) : 0;
;       const float b0 = trow[d0], b1 = trow[d1];
;       s0[i] = v0 ? s0[i] + b0 : -1e30f;
;       s1[i] = v1 ? s1[i] + b1 : -1e30f;
;     }
;     float alpha; bf16x8 pf[4];
;     const bool resc = softmax_tile(s0, s1, m, l, alpha, pf, lane, kt == 0, true);
.LBB0_1541:
	ds_read_b128 v[150:153], v123
	ds_read_b128 v[154:157], v123 offset:32
	ds_read_b128 v[158:161], v123 offset:8704
	ds_read_b128 v[162:165], v123 offset:8736
	ds_read_b128 v[166:169], v123 offset:64
	ds_read_b128 v[170:173], v123 offset:96
	ds_read_b128 v[174:177], v123 offset:8768
	ds_read_b128 v[178:181], v123 offset:8800
	s_waitcnt lgkmcnt(7)
	v_mfma_f32_32x32x16_bf16 v[48:63], v[150:153], v[64:67], v[220:235]
	s_waitcnt lgkmcnt(5)
	v_mfma_f32_32x32x16_bf16 v[32:47], v[158:161], v[64:67], v[220:235]
	v_mfma_f32_32x32x16_bf16 v[48:63], v[154:157], v[68:71], v[48:63]
	s_waitcnt lgkmcnt(4)
	v_mfma_f32_32x32x16_bf16 v[32:47], v[162:165], v[68:71], v[32:47]
	s_waitcnt lgkmcnt(3)
	v_mfma_f32_32x32x16_bf16 v[48:63], v[166:169], v[72:75], v[48:63]
	s_waitcnt lgkmcnt(1)
	v_mfma_f32_32x32x16_bf16 v[32:47], v[174:177], v[72:75], v[32:47]
	v_mfma_f32_32x32x16_bf16 v[48:63], v[170:173], v[76:79], v[48:63]
	s_waitcnt lgkmcnt(0)
	v_mfma_f32_32x32x16_bf16 v[32:47], v[178:181], v[76:79], v[32:47]
	s_bitcmp1_b32 s100, 6
	s_cbranch_scc1 .Lna_el_q1
	v_add_u32_e32 v149, s9, v130
	ds_read_b32 v150, v149 offset:868
	ds_read_b32 v151, v149 offset:872
	ds_read_b32 v152, v149 offset:876
	ds_read_b32 v153, v149 offset:880
	ds_read_b32 v154, v149 offset:900
	ds_read_b32 v155, v149 offset:904
	ds_read_b32 v156, v149 offset:908
	ds_read_b32 v157, v149 offset:912
	ds_read_b32 v158, v149 offset:932
	ds_read_b32 v159, v149 offset:936
	ds_read_b32 v160, v149 offset:940
	ds_read_b32 v161, v149 offset:944
	ds_read_b32 v162, v149 offset:964
	ds_read_b32 v163, v149 offset:968
	ds_read_b32 v164, v149 offset:972
	ds_read_b32 v165, v149 offset:976
	ds_read_b32 v166, v149 offset:996
	ds_read_b32 v167, v149 offset:1000
	ds_read_b32 v168, v149 offset:1004
	ds_read_b32 v169, v149 offset:1008
	s_waitcnt lgkmcnt(0)
	s_nop 7
	v_add_f32_e32 v48, v48, v150
	v_cndmask_b32_e64 v48, v195, v48, s[76:77]
	v_exp_f32_e32 v48, v48
	v_add_f32_e32 v49, v49, v151
	v_cndmask_b32_e64 v49, v195, v49, s[90:91]
	v_exp_f32_e32 v49, v49
	v_add_f32_e32 v50, v50, v152
	v_cndmask_b32_e64 v50, v195, v50, s[96:97]
	v_exp_f32_e32 v50, v50
	v_add_f32_e32 v51, v51, v153
	v_cndmask_b32_e64 v51, v195, v51, s[70:71]
	v_exp_f32_e32 v51, v51
	v_add_f32_e32 v52, v52, v154
	v_cndmask_b32_e64 v52, v195, v52, s[64:65]
	v_exp_f32_e32 v52, v52
	v_add_f32_e32 v53, v53, v155
	v_cndmask_b32_e64 v53, v195, v53, s[66:67]
	v_exp_f32_e32 v53, v53
	v_add_f32_e32 v54, v54, v156
	v_cndmask_b32_e64 v54, v195, v54, s[60:61]
	v_exp_f32_e32 v54, v54
	v_add_f32_e32 v55, v55, v157
	v_cndmask_b32_e64 v55, v195, v55, s[68:69]
	v_exp_f32_e32 v55, v55
	v_add_f32_e32 v56, v56, v158
	v_cndmask_b32_e64 v56, v195, v56, s[52:53]
	v_exp_f32_e32 v56, v56
	v_add_f32_e32 v57, v57, v159
	v_cndmask_b32_e64 v57, v195, v57, s[54:55]
	v_exp_f32_e32 v57, v57
	v_add_f32_e32 v58, v58, v160
	v_cndmask_b32_e64 v58, v195, v58, s[40:41]
	v_exp_f32_e32 v58, v58
	v_add_f32_e32 v59, v59, v161
	v_cndmask_b32_e64 v59, v195, v59, s[42:43]
	v_exp_f32_e32 v59, v59
	v_add_f32_e32 v60, v60, v162
	v_cndmask_b32_e64 v60, v195, v60, s[36:37]
	v_exp_f32_e32 v60, v60
	v_add_f32_e32 v61, v61, v163
	v_cndmask_b32_e64 v61, v195, v61, s[46:47]
	v_exp_f32_e32 v61, v61
	v_add_f32_e32 v62, v62, v164
	v_cndmask_b32_e64 v62, v195, v62, s[86:87]
	v_exp_f32_e32 v62, v62
	v_add_f32_e32 v63, v63, v165
	v_cndmask_b32_e64 v63, v195, v63, s[4:5]
	v_exp_f32_e32 v63, v63
	v_add_f32_e32 v32, v32, v166
	v_cndmask_b32_e64 v32, v195, v32, s[78:79]
	v_exp_f32_e32 v32, v32
	v_add_f32_e32 v33, v33, v167
	v_cndmask_b32_e64 v33, v195, v33, s[92:93]
	v_exp_f32_e32 v33, v33
	v_add_f32_e32 v34, v34, v168
	v_cndmask_b32_e64 v34, v195, v34, s[94:95]
	v_exp_f32_e32 v34, v34
	v_add_f32_e32 v35, v35, v169
	v_cndmask_b32_e64 v35, v195, v35, s[72:73]
	v_exp_f32_e32 v35, v35
	v_add_f32_e32 v149, v48, v49
	v_add_f32_e32 v149, v149, v50
	v_add_f32_e32 v149, v149, v51
	v_add_f32_e32 v149, v149, v52
	v_add_f32_e32 v149, v149, v53
	v_add_f32_e32 v149, v149, v54
	v_add_f32_e32 v149, v149, v55
	v_add_f32_e32 v149, v149, v56
	v_add_f32_e32 v149, v149, v57
	v_add_f32_e32 v149, v149, v58
	v_add_f32_e32 v149, v149, v59
	v_add_f32_e32 v149, v149, v60
	v_add_f32_e32 v149, v149, v61
	v_add_f32_e32 v149, v149, v62
	v_add_f32_e32 v149, v149, v63
	v_add_f32_e32 v149, v149, v32
	v_add_f32_e32 v149, v149, v33
	v_add_f32_e32 v149, v149, v34
	v_add_f32_e32 v149, v149, v35
	v_cvt_pk_bf16_f32 v36, v48, v49
	v_cvt_pk_bf16_f32 v37, v50, v51
	v_cvt_pk_bf16_f32 v38, v52, v53
	v_cvt_pk_bf16_f32 v39, v54, v55
	v_cvt_pk_bf16_f32 v40, v56, v57
	v_cvt_pk_bf16_f32 v41, v58, v59
	v_cvt_pk_bf16_f32 v42, v60, v61
	v_cvt_pk_bf16_f32 v43, v62, v63
	v_cvt_pk_bf16_f32 v44, v32, v33
	v_cvt_pk_bf16_f32 v45, v34, v35
	v_mov_b32_e32 v46, 0
	v_mov_b32_e32 v47, 0
	v_mov_b32_e32 v33, v149
	s_branch .Lna_el_done

; DI f32x16 mfma32(bf16x8 a, bf16x8 b, f32x16 c) { return __builtin_amdgcn_mfma_f32_32x32x16_bf16(a, b, c, 0, 0, 0); }
; DI bool softmax_tile(f32x16& s0, f32x16& s1, float& m, float& l, float& alpha, bf16x8* pf, int lane, bool first, bool check) {
;     ...
;   if (!check) return false;
;   const float rsum = sum + shx(sum, 32, lane);
;   const bool trig = rsum > 65536.f;
;   const bool resc = (__builtin_amdgcn_ballot_w64(trig) != 0ull);
;   alpha = 1.f;
;   if (resc) {
;     const float d = trig ? (float)(__builtin_amdgcn_frexp_expf(rsum) - 7) : 0.f;
;     alpha = __builtin_amdgcn_exp2f(-d);
;     m += d; l *= alpha;
;   }
;   return resc;
; DI void attn_na_unit(const Params& p, int li, int b, int r, int hp, char* smem) {
;     ...
;     {
;       bf16x8 vf[8];
; #pragma unroll
;       for (int s = 0; s < 4; ++s) { vf[2 * s] = ld_vfrag_tr(vs, vbase, VR, 16 * s, hs * 64); vf[2 * s + 1] = ld_vfrag_tr(vs, vbase, VR, 16 * s, hs * 64 + 32); }
;       __builtin_amdgcn_sched_barrier(0); __builtin_amdgcn_s_setprio(1);
; #pragma unroll
;       for (int s = 0; s < 4; ++s) { O0 = mfma32(vf[2 * s], pf[s], O0); O1 = mfma32(vf[2 * s + 1], pf[s], O1); }
.Lna_rd_q0:
	ds_bpermute_b32 v32, v124, v33
	s_waitcnt lgkmcnt(0)
	v_add_f32_e32 v32, v33, v32
	v_cmp_lt_f32_e32 vcc, s88, v32
	v_frexp_exp_i32_f32_e32 v32, v32
	v_add_u32_e32 v32, -7, v32
	v_cvt_f32_i32_e32 v32, v32
	s_cmp_eq_u64 vcc, 0
	s_cselect_b64 s[6:7], -1, 0
	v_cndmask_b32_e32 v34, 0, v32, vcc
	v_exp_f32_e64 v32, -v34
	s_bitcmp1_b32 s100, 6
	s_cbranch_scc1 .Lna_mm_q1
	v_mfma_f32_32x32x16_bf16 v[16:31], v[52:55], v[36:39], v[16:31]
	v_mfma_f32_32x32x16_bf16 v[0:15], v[56:59], v[36:39], v[0:15]

; DI f32x16 mfma32(bf16x8 a, bf16x8 b, f32x16 c) { return __builtin_amdgcn_mfma_f32_32x32x16_bf16(a, b, c, 0, 0, 0); }
; DI void attn_na_unit(const Params& p, int li, int b, int r, int hp, char* smem) {
;     ...
;       for (int s = 0; s < 4; ++s) { O0 = mfma32(vf[2 * s], pf[s], O0); O1 = mfma32(vf[2 * s + 1], pf[s], O1); }
;     __builtin_amdgcn_s_setprio(0);
; }
;     if (resc) { scale16(O0, alpha); scale16(O1, alpha); }
.Lna_mm_q0:
	s_cbranch_vccz .LBB0_1538
	s_nop 8
	v_pk_mul_f32 v[30:31], v[32:33], v[30:31] op_sel_hi:[0,1]
	v_pk_mul_f32 v[28:29], v[32:33], v[28:29] op_sel_hi:[0,1]
	v_pk_mul_f32 v[26:27], v[32:33], v[26:27] op_sel_hi:[0,1]
	v_pk_mul_f32 v[24:25], v[32:33], v[24:25] op_sel_hi:[0,1]
	v_pk_mul_f32 v[22:23], v[32:33], v[22:23] op_sel_hi:[0,1]
	v_pk_mul_f32 v[20:21], v[32:33], v[20:21] op_sel_hi:[0,1]
	v_pk_mul_f32 v[18:19], v[32:33], v[18:19] op_sel_hi:[0,1]
	v_pk_mul_f32 v[16:17], v[32:33], v[16:17] op_sel_hi:[0,1]
	v_pk_mul_f32 v[14:15], v[32:33], v[14:15] op_sel_hi:[0,1]
	v_pk_mul_f32 v[12:13], v[32:33], v[12:13] op_sel_hi:[0,1]
	v_pk_mul_f32 v[10:11], v[32:33], v[10:11] op_sel_hi:[0,1]
	v_pk_mul_f32 v[8:9], v[32:33], v[8:9] op_sel_hi:[0,1]
	v_pk_mul_f32 v[6:7], v[32:33], v[6:7] op_sel_hi:[0,1]
	v_pk_mul_f32 v[4:5], v[32:33], v[4:5] op_sel_hi:[0,1]
	v_pk_mul_f32 v[2:3], v[32:33], v[2:3] op_sel_hi:[0,1]
	v_pk_mul_f32 v[0:1], v[32:33], v[0:1] op_sel_hi:[0,1]
	s_branch .LBB0_1538
